# dense softmax: per-tile row-max replaced by an overflow check on the row sum; exact path recomputes QK^T of the tile
# baseline (speedup 1.0000x reference)
; __device__ __forceinline__ void partialSM(f32x16& p0, f32x16& p1, float& m_reg, float& mn, float& alpha) {
;   constexpr float C = SCALE * 1.4426950408889634f;
;   float pmax = p0[0];
; #pragma unroll
;   for (int r = 1; r < 16; ++r) pmax = fmaxf(pmax, p0[r]);
; #pragma unroll
;   for (int r = 0; r < 16; ++r) pmax = fmaxf(pmax, p1[r]);
;   { auto rr = __builtin_amdgcn_permlane32_swap(__float_as_uint(pmax), __float_as_uint(pmax), false, false);
;     pmax = fmaxf(__uint_as_float(rr[0]), __uint_as_float(rr[1])); }
;   if (__builtin_expect(__all(pmax - m_reg <= THR / SCALE), 1)) { mn = m_reg; alpha = 1.f; }
;   else { mn = fmaxf(m_reg, pmax); alpha = __builtin_amdgcn_exp2f((m_reg - mn) * C); m_reg = mn; }
;   float mnC = -mn * C;
; #pragma unroll
;   for (int r = 0; r < 16; ++r) p0[r] = fmaf(p0[r], C, mnC);
; #pragma unroll
;   for (int r = 0; r < 16; ++r) p1[r] = fmaf(p1[r], C, mnC);
; #pragma unroll
;   for (int r = 0; r < 16; ++r) p0[r] = __builtin_amdgcn_exp2f(p0[r]);
; }
; __device__ __forceinline__ void finishSM(f32x16& p0, f32x16& p1, float alpha, float& l_reg, bf16x8& pa0, bf16x8& pa1, bf16x8& pa2, bf16x8& pa3) {
; #pragma unroll
;   for (int r = 0; r < 16; ++r) p1[r] = __builtin_amdgcn_exp2f(p1[r]);
;   float ps = 0;
; #pragma unroll
;   for (int r = 0; r < 16; ++r) ps += p0[r];
; #pragma unroll
;   for (int r = 0; r < 16; ++r) ps += p1[r];
;   { auto rr = __builtin_amdgcn_permlane32_swap(__float_as_uint(ps), __float_as_uint(ps), false, false);
;     ps = __uint_as_float(rr[0]) + __uint_as_float(rr[1]); }
; __device__ __forceinline__ void qkt(f32x16& p0, f32x16& p1, const bf16_t* Ks, const bf16x8* qr, int r32, int hi) {
;   p0 = f32x16{}; p1 = f32x16{};
; #pragma unroll
;   for (int d0 = 0; d0 < 8; ++d0) { int cb = (d0 * 16 + hi * 8) * 2;
;     bf16x8 b0 = *reinterpret_cast<const bf16x8*>((const char*)Ks + KSWZ(r32, cb));
;     bf16x8 b1 = *reinterpret_cast<const bf16x8*>((const char*)Ks + KSWZ(32 + r32, cb));
;     p0 = __builtin_amdgcn_mfma_f32_32x32x16_bf16(b0, qr[d0], p0, 0, 0, 0);
;     p1 = __builtin_amdgcn_mfma_f32_32x32x16_bf16(b1, qr[d0], p1, 0, 0, 0); }
; }
.Lda_y0:
	s_barrier
	v_fma_f32 v80, v80, s92, v214
	v_fma_f32 v81, v81, s92, v214
	v_fma_f32 v82, v82, s92, v214
	v_fma_f32 v83, v83, s92, v214
	v_fma_f32 v84, v84, s92, v214
	v_fma_f32 v85, v85, s92, v214
	v_fma_f32 v86, v86, s92, v214
	v_fma_f32 v87, v87, s92, v214
	v_fma_f32 v88, v88, s92, v214
	v_fma_f32 v89, v89, s92, v214
	v_fma_f32 v90, v90, s92, v214
	v_fma_f32 v91, v91, s92, v214
	v_fma_f32 v92, v92, s92, v214
	v_fma_f32 v93, v93, s92, v214
	v_fma_f32 v94, v94, s92, v214
	v_fma_f32 v95, v95, s92, v214
	v_fma_f32 v64, v64, s92, v214
	v_fma_f32 v65, v65, s92, v214
	v_fma_f32 v66, v66, s92, v214
	v_fma_f32 v67, v67, s92, v214
	v_fma_f32 v68, v68, s92, v214
	v_fma_f32 v69, v69, s92, v214
	v_fma_f32 v70, v70, s92, v214
	v_fma_f32 v71, v71, s92, v214
	v_fma_f32 v72, v72, s92, v214
	v_fma_f32 v73, v73, s92, v214
	v_fma_f32 v74, v74, s92, v214
	v_fma_f32 v75, v75, s92, v214
	v_fma_f32 v76, v76, s92, v214
	v_fma_f32 v77, v77, s92, v214
	v_fma_f32 v78, v78, s92, v214
	v_fma_f32 v79, v79, s92, v214
	v_exp_f32_e32 v80, v80
	v_exp_f32_e32 v81, v81
	v_exp_f32_e32 v82, v82
	v_exp_f32_e32 v83, v83
	v_exp_f32_e32 v84, v84
	v_exp_f32_e32 v85, v85
	v_exp_f32_e32 v86, v86
	v_exp_f32_e32 v87, v87
	v_exp_f32_e32 v88, v88
	v_exp_f32_e32 v89, v89
	v_exp_f32_e32 v90, v90
	v_exp_f32_e32 v91, v91
	v_exp_f32_e32 v92, v92
	v_exp_f32_e32 v93, v93
	v_exp_f32_e32 v94, v94
	v_exp_f32_e32 v95, v95
	v_exp_f32_e32 v64, v64
	v_exp_f32_e32 v65, v65
	v_exp_f32_e32 v66, v66
	v_exp_f32_e32 v67, v67
	v_exp_f32_e32 v68, v68
	v_exp_f32_e32 v69, v69
	v_exp_f32_e32 v70, v70
	v_exp_f32_e32 v71, v71
	v_exp_f32_e32 v72, v72
	v_exp_f32_e32 v73, v73
	v_exp_f32_e32 v74, v74
	v_exp_f32_e32 v75, v75
	v_exp_f32_e32 v76, v76
	v_exp_f32_e32 v77, v77
	v_exp_f32_e32 v78, v78
	v_exp_f32_e32 v79, v79
	v_add_f32_e32 v190, v80, v81
	v_add_f32_e32 v191, v82, v83
	v_add_f32_e32 v190, v190, v84
	v_add_f32_e32 v191, v191, v85
	v_add_f32_e32 v190, v190, v86
	v_add_f32_e32 v191, v191, v87
	v_add_f32_e32 v190, v190, v88
	v_add_f32_e32 v191, v191, v89
	v_add_f32_e32 v190, v190, v90
	v_add_f32_e32 v191, v191, v91
	v_add_f32_e32 v190, v190, v92
	v_add_f32_e32 v191, v191, v93
	v_add_f32_e32 v190, v190, v94
	v_add_f32_e32 v191, v191, v95
	v_add_f32_e32 v190, v190, v64
	v_add_f32_e32 v191, v191, v65
	v_add_f32_e32 v190, v190, v66
	v_add_f32_e32 v191, v191, v67
	v_add_f32_e32 v190, v190, v68
	v_add_f32_e32 v191, v191, v69
	v_add_f32_e32 v190, v190, v70
	v_add_f32_e32 v191, v191, v71
	v_add_f32_e32 v190, v190, v72
	v_add_f32_e32 v191, v191, v73
	v_add_f32_e32 v190, v190, v74
	v_add_f32_e32 v191, v191, v75
	v_add_f32_e32 v190, v190, v76
	v_add_f32_e32 v191, v191, v77
	v_add_f32_e32 v190, v190, v78
	v_add_f32_e32 v191, v191, v79
	v_add_f32_e32 v190, v190, v191
	v_cmp_ge_f32_e32 vcc, 0x453a4f54, v190
	s_nop 0
	s_cmp_eq_u64 vcc, exec
	s_cbranch_scc1 .Lda_pack_0
	ds_read_b128 v[150:153], v204 offset:0
	ds_read_b128 v[154:157], v204 offset:8192
	ds_read_b128 v[158:161], v205 offset:0
	ds_read_b128 v[162:165], v205 offset:8192
	ds_read_b128 v[228:231], v206 offset:0
	ds_read_b128 v[232:235], v206 offset:8192
	ds_read_b128 v[236:239], v207 offset:0
	ds_read_b128 v[240:243], v207 offset:8192
	s_waitcnt lgkmcnt(6)
	v_mfma_f32_32x32x16_bf16 v[80:95], v[150:153], v[130:133], 0
	v_mfma_f32_32x32x16_bf16 v[64:79], v[154:157], v[130:133], 0
	ds_read_b128 v[150:153], v208 offset:0
	ds_read_b128 v[154:157], v208 offset:8192
	s_waitcnt lgkmcnt(6)
	v_mfma_f32_32x32x16_bf16 v[80:95], v[158:161], v[126:129], v[80:95]
	v_mfma_f32_32x32x16_bf16 v[64:79], v[162:165], v[126:129], v[64:79]
	ds_read_b128 v[158:161], v209 offset:0
	ds_read_b128 v[162:165], v209 offset:8192
	s_waitcnt lgkmcnt(6)
	v_mfma_f32_32x32x16_bf16 v[80:95], v[228:231], v[122:125], v[80:95]
	v_mfma_f32_32x32x16_bf16 v[64:79], v[232:235], v[122:125], v[64:79]
	ds_read_b128 v[228:231], v210 offset:0
	ds_read_b128 v[232:235], v210 offset:8192
	s_waitcnt lgkmcnt(6)
	v_mfma_f32_32x32x16_bf16 v[80:95], v[236:239], v[118:121], v[80:95]
	v_mfma_f32_32x32x16_bf16 v[64:79], v[240:243], v[118:121], v[64:79]
	ds_read_b128 v[236:239], v211 offset:0
	ds_read_b128 v[240:243], v211 offset:8192
	s_waitcnt lgkmcnt(6)
	v_mfma_f32_32x32x16_bf16 v[80:95], v[150:153], v[114:117], v[80:95]
	v_mfma_f32_32x32x16_bf16 v[64:79], v[154:157], v[114:117], v[64:79]
	s_waitcnt lgkmcnt(4)
	v_mfma_f32_32x32x16_bf16 v[80:95], v[158:161], v[110:113], v[80:95]
	v_mfma_f32_32x32x16_bf16 v[64:79], v[162:165], v[110:113], v[64:79]
	s_waitcnt lgkmcnt(2)
	v_mfma_f32_32x32x16_bf16 v[80:95], v[228:231], v[106:109], v[80:95]
	v_mfma_f32_32x32x16_bf16 v[64:79], v[232:235], v[106:109], v[64:79]
	s_waitcnt lgkmcnt(0)
	v_mfma_f32_32x32x16_bf16 v[80:95], v[236:239], v[102:105], v[80:95]
	v_mfma_f32_32x32x16_bf16 v[64:79], v[240:243], v[102:105], v[64:79]
	s_nop 12
	v_max3_f32 v190, v80, v81, v82
	v_max3_f32 v191, v64, v65, v66
	v_max3_f32 v190, v190, v83, v84
	v_max3_f32 v191, v191, v67, v68
	v_max3_f32 v190, v190, v85, v86
	v_max3_f32 v191, v191, v69, v70
	v_max3_f32 v190, v190, v87, v88
	v_max3_f32 v191, v191, v71, v72
	v_max3_f32 v190, v190, v89, v90
	v_max3_f32 v191, v191, v73, v74
	v_max3_f32 v190, v190, v91, v92
	v_max3_f32 v191, v191, v75, v76
	v_max3_f32 v190, v190, v93, v94
	v_max3_f32 v191, v191, v77, v78
	v_max3_f32 v190, v190, v95, v79
	v_max_f32_e32 v190, v190, v191
	v_mov_b32_e32 v191, v190
	s_nop 1
	v_permlane32_swap_b32_e32 v190, v191
	s_nop 0
	v_max_f32_e32 v212, v190, v191
	v_sub_f32_e32 v215, v212, v174
	v_cmp_ge_f32_e32 vcc, s86, v215
	s_nop 0
	s_cmp_eq_u64 vcc, exec
	s_cbranch_scc1 .Lda_slow2_0
; __device__ __forceinline__ void partialSM(f32x16& p0, f32x16& p1, float& m_reg, float& mn, float& alpha) {
;     ...
;   else { mn = fmaxf(m_reg, pmax); alpha = __builtin_amdgcn_exp2f((m_reg - mn) * C); m_reg = mn; }
;   float mnC = -mn * C;
; #pragma unroll
;   for (int r = 0; r < 16; ++r) p0[r] = fmaf(p0[r], C, mnC);
; #pragma unroll
;   for (int r = 0; r < 16; ++r) p1[r] = fmaf(p1[r], C, mnC);
; #pragma unroll
;   for (int r = 0; r < 16; ++r) p0[r] = __builtin_amdgcn_exp2f(p0[r]);
; }
; __device__ __forceinline__ void finishSM(f32x16& p0, f32x16& p1, float alpha, float& l_reg, bf16x8& pa0, bf16x8& pa1, bf16x8& pa2, bf16x8& pa3) {
; #pragma unroll
;   for (int r = 0; r < 16; ++r) p1[r] = __builtin_amdgcn_exp2f(p1[r]);
;   float ps = 0;
; #pragma unroll
;   for (int r = 0; r < 16; ++r) ps += p0[r];
; #pragma unroll
;   for (int r = 0; r < 16; ++r) ps += p1[r];
;   { auto rr = __builtin_amdgcn_permlane32_swap(__float_as_uint(ps), __float_as_uint(ps), false, false);
;     ps = __uint_as_float(rr[0]) + __uint_as_float(rr[1]); }
;   l_reg = l_reg * alpha + ps;
;     ...
;   PK4(p0, 0, pa0); PK4(p0, 8, pa1); PK4(p1, 0, pa2); PK4(p1, 8, pa3);
	v_max_f32_e32 v191, v174, v212
	v_sub_f32_e32 v215, v174, v191
	v_mul_f32_e32 v215, s92, v215
	v_exp_f32_e32 v213, v215
	v_mov_b32_e32 v174, v191
	v_mul_f32_e32 v214, 0xbe0293ee, v174
	v_mul_f32_e32 v175, v175, v213
	s_and_saveexec_b64 s[12:13], s[40:41]
	ds_write_b32 v199, v213 offset:128
	s_or_b64 exec, exec, s[12:13]
	s_waitcnt lgkmcnt(0)
	v_add_u32_e32 v215, v99, v96
	ds_read_b128 v[228:231], v215 offset:128
	ds_read_b128 v[232:235], v215 offset:160
	ds_read_b128 v[236:239], v215 offset:192
	ds_read_b128 v[240:243], v215 offset:224
	s_waitcnt lgkmcnt(0)
	v_pk_mul_f32 v[0:1], v[0:1], v[228:229]
	v_pk_mul_f32 v[2:3], v[2:3], v[230:231]
	v_pk_mul_f32 v[4:5], v[4:5], v[232:233]
	v_pk_mul_f32 v[6:7], v[6:7], v[234:235]
	v_pk_mul_f32 v[8:9], v[8:9], v[236:237]
	v_pk_mul_f32 v[10:11], v[10:11], v[238:239]
	v_pk_mul_f32 v[12:13], v[12:13], v[240:241]
	v_pk_mul_f32 v[14:15], v[14:15], v[242:243]
	v_pk_mul_f32 v[48:49], v[48:49], v[228:229]
	v_pk_mul_f32 v[50:51], v[50:51], v[230:231]
	v_pk_mul_f32 v[52:53], v[52:53], v[232:233]
	v_pk_mul_f32 v[54:55], v[54:55], v[234:235]
	v_pk_mul_f32 v[56:57], v[56:57], v[236:237]
	v_pk_mul_f32 v[58:59], v[58:59], v[238:239]
	v_pk_mul_f32 v[60:61], v[60:61], v[240:241]
	v_pk_mul_f32 v[62:63], v[62:63], v[242:243]
	v_pk_mul_f32 v[32:33], v[32:33], v[228:229]
	v_pk_mul_f32 v[34:35], v[34:35], v[230:231]
	v_pk_mul_f32 v[36:37], v[36:37], v[232:233]
	v_pk_mul_f32 v[38:39], v[38:39], v[234:235]
	v_pk_mul_f32 v[40:41], v[40:41], v[236:237]
	v_pk_mul_f32 v[42:43], v[42:43], v[238:239]
	v_pk_mul_f32 v[44:45], v[44:45], v[240:241]
	v_pk_mul_f32 v[46:47], v[46:47], v[242:243]
	v_pk_mul_f32 v[16:17], v[16:17], v[228:229]
	v_pk_mul_f32 v[18:19], v[18:19], v[230:231]
	v_pk_mul_f32 v[20:21], v[20:21], v[232:233]
	v_pk_mul_f32 v[22:23], v[22:23], v[234:235]
	v_pk_mul_f32 v[24:25], v[24:25], v[236:237]
	v_pk_mul_f32 v[26:27], v[26:27], v[238:239]
	v_pk_mul_f32 v[28:29], v[28:29], v[240:241]
	v_pk_mul_f32 v[30:31], v[30:31], v[242:243]
.Lda_slow2_0:
	v_fma_f32 v80, v80, s92, v214
	v_fma_f32 v81, v81, s92, v214
	v_fma_f32 v82, v82, s92, v214
	v_fma_f32 v83, v83, s92, v214
	v_fma_f32 v84, v84, s92, v214
	v_fma_f32 v85, v85, s92, v214
	v_fma_f32 v86, v86, s92, v214
	v_fma_f32 v87, v87, s92, v214
	v_fma_f32 v88, v88, s92, v214
	v_fma_f32 v89, v89, s92, v214
	v_fma_f32 v90, v90, s92, v214
	v_fma_f32 v91, v91, s92, v214
	v_fma_f32 v92, v92, s92, v214
	v_fma_f32 v93, v93, s92, v214
	v_fma_f32 v94, v94, s92, v214
	v_fma_f32 v95, v95, s92, v214
	v_fma_f32 v64, v64, s92, v214
	v_fma_f32 v65, v65, s92, v214
	v_fma_f32 v66, v66, s92, v214
	v_fma_f32 v67, v67, s92, v214
	v_fma_f32 v68, v68, s92, v214
	v_fma_f32 v69, v69, s92, v214
	v_fma_f32 v70, v70, s92, v214
	v_fma_f32 v71, v71, s92, v214
	v_fma_f32 v72, v72, s92, v214
	v_fma_f32 v73, v73, s92, v214
	v_fma_f32 v74, v74, s92, v214
	v_fma_f32 v75, v75, s92, v214
	v_fma_f32 v76, v76, s92, v214
	v_fma_f32 v77, v77, s92, v214
	v_fma_f32 v78, v78, s92, v214
	v_fma_f32 v79, v79, s92, v214
	v_exp_f32_e32 v80, v80
	v_exp_f32_e32 v81, v81
	v_exp_f32_e32 v82, v82
	v_exp_f32_e32 v83, v83
	v_exp_f32_e32 v84, v84
	v_exp_f32_e32 v85, v85
	v_exp_f32_e32 v86, v86
	v_exp_f32_e32 v87, v87
	v_exp_f32_e32 v88, v88
	v_exp_f32_e32 v89, v89
	v_exp_f32_e32 v90, v90
	v_exp_f32_e32 v91, v91
	v_exp_f32_e32 v92, v92
	v_exp_f32_e32 v93, v93
	v_exp_f32_e32 v94, v94
	v_exp_f32_e32 v95, v95
	v_exp_f32_e32 v64, v64
	v_exp_f32_e32 v65, v65
	v_exp_f32_e32 v66, v66
	v_exp_f32_e32 v67, v67
	v_exp_f32_e32 v68, v68
	v_exp_f32_e32 v69, v69
	v_exp_f32_e32 v70, v70
	v_exp_f32_e32 v71, v71
	v_exp_f32_e32 v72, v72
	v_exp_f32_e32 v73, v73
	v_exp_f32_e32 v74, v74
	v_exp_f32_e32 v75, v75
	v_exp_f32_e32 v76, v76
	v_exp_f32_e32 v77, v77
	v_exp_f32_e32 v78, v78
	v_exp_f32_e32 v79, v79
	v_add_f32_e32 v190, v80, v81
	v_add_f32_e32 v191, v82, v83
	v_add_f32_e32 v190, v190, v84
	v_add_f32_e32 v191, v191, v85
	v_add_f32_e32 v190, v190, v86
	v_add_f32_e32 v191, v191, v87
	v_add_f32_e32 v190, v190, v88
	v_add_f32_e32 v191, v191, v89
	v_add_f32_e32 v190, v190, v90
	v_add_f32_e32 v191, v191, v91
	v_add_f32_e32 v190, v190, v92
	v_add_f32_e32 v191, v191, v93
	v_add_f32_e32 v190, v190, v94
	v_add_f32_e32 v191, v191, v95
	v_add_f32_e32 v190, v190, v64
	v_add_f32_e32 v191, v191, v65
	v_add_f32_e32 v190, v190, v66
	v_add_f32_e32 v191, v191, v67
	v_add_f32_e32 v190, v190, v68
	v_add_f32_e32 v191, v191, v69
	v_add_f32_e32 v190, v190, v70
	v_add_f32_e32 v191, v191, v71
	v_add_f32_e32 v190, v190, v72
	v_add_f32_e32 v191, v191, v73
	v_add_f32_e32 v190, v190, v74
	v_add_f32_e32 v191, v191, v75
	v_add_f32_e32 v190, v190, v76
	v_add_f32_e32 v191, v191, v77
	v_add_f32_e32 v190, v190, v78
	v_add_f32_e32 v191, v191, v79
	v_add_f32_e32 v190, v190, v191
.Lda_pack_0:
	v_add_f32_e32 v175, v175, v190
	v_cvt_pk_bf16_f32 v166, v80, v81
	v_cvt_pk_bf16_f32 v167, v82, v83
	v_cvt_pk_bf16_f32 v168, v84, v85
	v_cvt_pk_bf16_f32 v169, v86, v87
	v_cvt_pk_bf16_f32 v170, v88, v89
	v_cvt_pk_bf16_f32 v171, v90, v91
	v_cvt_pk_bf16_f32 v172, v92, v93
	v_cvt_pk_bf16_f32 v173, v94, v95
	v_cvt_pk_bf16_f32 v176, v64, v65
	v_cvt_pk_bf16_f32 v177, v66, v67
	v_cvt_pk_bf16_f32 v178, v68, v69
	v_cvt_pk_bf16_f32 v179, v70, v71
	v_cvt_pk_bf16_f32 v180, v72, v73
	v_cvt_pk_bf16_f32 v181, v74, v75
	v_cvt_pk_bf16_f32 v182, v76, v77
	v_cvt_pk_bf16_f32 v183, v78, v79
	v_permlane32_swap_b32_e32 v166, v168
	v_permlane32_swap_b32_e32 v167, v169
	v_permlane32_swap_b32_e32 v170, v172
	v_permlane32_swap_b32_e32 v171, v173
	v_permlane32_swap_b32_e32 v176, v178
	v_permlane32_swap_b32_e32 v177, v179
	v_permlane32_swap_b32_e32 v180, v182
	v_permlane32_swap_b32_e32 v181, v183
	s_add_u32 s31, s31, 1
	s_cmp_lt_u32 s31, 132
	s_cbranch_scc0 .Lda_skipk_0
	ds_read_b128 v[150:153], v204 offset:16384
	ds_read_b128 v[154:157], v204 offset:24576
	ds_read_b128 v[158:161], v205 offset:16384
	ds_read_b128 v[162:165], v205 offset:24576
	ds_read_b128 v[228:231], v206 offset:16384
	ds_read_b128 v[232:235], v206 offset:24576
	ds_read_b128 v[236:239], v207 offset:16384
	ds_read_b128 v[240:243], v207 offset:24576
; #define SBAR() __builtin_amdgcn_sched_barrier(0)
; __device__ __forceinline__ void qkt(f32x16& p0, f32x16& p1, const bf16_t* Ks, const bf16x8* qr, int r32, int hi) {
;   p0 = f32x16{}; p1 = f32x16{};
; #pragma unroll
;   for (int d0 = 0; d0 < 8; ++d0) { int cb = (d0 * 16 + hi * 8) * 2;
;     bf16x8 b0 = *reinterpret_cast<const bf16x8*>((const char*)Ks + KSWZ(r32, cb));
;     bf16x8 b1 = *reinterpret_cast<const bf16x8*>((const char*)Ks + KSWZ(32 + r32, cb));
;     p0 = __builtin_amdgcn_mfma_f32_32x32x16_bf16(b0, qr[d0], p0, 0, 0, 0);
;     p1 = __builtin_amdgcn_mfma_f32_32x32x16_bf16(b1, qr[d0], p1, 0, 0, 0); }
; }
; __device__ __forceinline__ int v_st(int k, int c) { const int kk = (k & ~0xC) | ((k & 4) << 1) | ((k & 8) >> 1); return ((kk >> 3) * 4 + (c >> 5)) * 512 + ((kk & 7) * 32 + (c & 31)) * 2; }
; __device__ __forceinline__ int v_rd_base(int lane) { return ((lane & 3) << 3) | (((lane >> 2) & 3) << 6) | (((lane >> 4) & 1) << 5) | (((lane >> 5) & 1) << 8); }
; template <int OFF> __device__ __forceinline__ s16x4 tr_read(int vb) {
;   s16x4 r; asm volatile("ds_read_b64_tr_b16 %0, %1 offset:%2" : "=&v"(r) : "v"(vb), "i"(OFF) : "memory"); return r;
; }
; template <int D0> __device__ __forceinline__ void pv_one(f32x16& od, int vb, bf16x8 pa0, bf16x8 pa1, bf16x8 pa2, bf16x8 pa3) {
;   const s16x4 l0 = tr_read<v_rd_off(D0, 0, 0)>(vb), h0 = tr_read<v_rd_off(D0, 0, 1)>(vb), l1 = tr_read<v_rd_off(D0, 1, 0)>(vb), h1 = tr_read<v_rd_off(D0, 1, 1)>(vb);
;   const s16x4 l2 = tr_read<v_rd_off(D0, 2, 0)>(vb), h2 = tr_read<v_rd_off(D0, 2, 1)>(vb), l3 = tr_read<v_rd_off(D0, 3, 0)>(vb), h3 = tr_read<v_rd_off(D0, 3, 1)>(vb);
;   asm volatile("s_waitcnt lgkmcnt(0)" ::: "memory"); SBAR();
;     ...
;   od = __builtin_amdgcn_mfma_f32_32x32x16_bf16(pa0, PK(l0, h0), od, 0, 0, 0);
;   od = __builtin_amdgcn_mfma_f32_32x32x16_bf16(pa1, PK(l1, h1), od, 0, 0, 0);
;   od = __builtin_amdgcn_mfma_f32_32x32x16_bf16(pa2, PK(l2, h2), od, 0, 0, 0);
;   od = __builtin_amdgcn_mfma_f32_32x32x16_bf16(pa3, PK(l3, h3), od, 0, 0, 0);
;     ...
; }
; __device__ __forceinline__ void pv_d0(f32x16* o, int vb, bf16x8 pa0, bf16x8 pa1, bf16x8 pa2, bf16x8 pa3) {
;   pv_one<0>(o[0], vb, pa0, pa1, pa2, pa3); pv_one<1>(o[1], vb, pa0, pa1, pa2, pa3); pv_one<2>(o[2], vb, pa0, pa1, pa2, pa3); pv_one<3>(o[3], vb, pa0, pa1, pa2, pa3);
.Lda_skipk_0:
	s_barrier
	s_setprio 3
	s_waitcnt vmcnt(4)
	ds_write_b128 v197, v[186:189] offset:49152
	ds_write_b128 v197, v[220:223] offset:57344
	ds_write_b128 v185, v[246:249] offset:49152
	ds_write_b128 v185, v[200:203] offset:57344
	s_waitcnt lgkmcnt(10)
	v_mfma_f32_32x32x16_bf16 v[80:95], v[150:153], v[130:133], 0
	v_mfma_f32_32x32x16_bf16 v[64:79], v[154:157], v[130:133], 0
	global_load_dwordx4 v[186:189], v184, s[16:17]
	global_load_dwordx4 v[220:223], v184, s[2:3]
	global_load_dwordx4 v[246:249], v184, s[14:15]
	global_load_dwordx4 v[200:203], v184, s[10:11]
	s_add_u32 s16, s16, 0x60000
	s_addc_u32 s17, s17, 0
	s_add_u32 s2, s2, 0x60000
	s_addc_u32 s3, s3, 0
	s_add_u32 s14, s14, 0x60000
	s_addc_u32 s15, s15, 0
	s_add_u32 s10, s10, 0x60000
	s_addc_u32 s11, s11, 0
	ds_read_b128 v[150:153], v208 offset:16384
	ds_read_b128 v[154:157], v208 offset:24576
	s_waitcnt lgkmcnt(10)
	v_mfma_f32_32x32x16_bf16 v[80:95], v[158:161], v[126:129], v[80:95]
	v_mfma_f32_32x32x16_bf16 v[64:79], v[162:165], v[126:129], v[64:79]
	ds_read_b128 v[158:161], v209 offset:16384
	ds_read_b128 v[162:165], v209 offset:24576
	s_waitcnt lgkmcnt(10)
	v_mfma_f32_32x32x16_bf16 v[80:95], v[228:231], v[122:125], v[80:95]
	v_mfma_f32_32x32x16_bf16 v[64:79], v[232:235], v[122:125], v[64:79]
	ds_read_b128 v[228:231], v210 offset:16384
	ds_read_b128 v[232:235], v210 offset:24576
	s_waitcnt lgkmcnt(10)
	v_mfma_f32_32x32x16_bf16 v[80:95], v[236:239], v[118:121], v[80:95]
	v_mfma_f32_32x32x16_bf16 v[64:79], v[240:243], v[118:121], v[64:79]
	ds_read_b128 v[236:239], v211 offset:16384
	ds_read_b128 v[240:243], v211 offset:24576
	s_waitcnt lgkmcnt(6)
	v_mfma_f32_32x32x16_bf16 v[80:95], v[150:153], v[114:117], v[80:95]
	v_mfma_f32_32x32x16_bf16 v[64:79], v[154:157], v[114:117], v[64:79]
	ds_read_b64_tr_b16 v[150:151], v196 offset:0
	ds_read_b64_tr_b16 v[152:153], v196 offset:2048
	ds_read_b64_tr_b16 v[154:155], v196 offset:4096
	ds_read_b64_tr_b16 v[156:157], v196 offset:6144
	s_waitcnt lgkmcnt(8)
	v_mfma_f32_32x32x16_bf16 v[80:95], v[158:161], v[110:113], v[80:95]
	v_mfma_f32_32x32x16_bf16 v[64:79], v[162:165], v[110:113], v[64:79]
	ds_read_b64_tr_b16 v[158:159], v196 offset:8192
	ds_read_b64_tr_b16 v[160:161], v196 offset:10240
	ds_read_b64_tr_b16 v[162:163], v196 offset:12288
	ds_read_b64_tr_b16 v[164:165], v196 offset:14336
	s_waitcnt lgkmcnt(10)
	v_mfma_f32_32x32x16_bf16 v[80:95], v[228:231], v[106:109], v[80:95]
	v_mfma_f32_32x32x16_bf16 v[64:79], v[232:235], v[106:109], v[64:79]
	ds_read_b64_tr_b16 v[228:229], v196 offset:512
	ds_read_b64_tr_b16 v[230:231], v196 offset:2560
	ds_read_b64_tr_b16 v[232:233], v196 offset:4608
	ds_read_b64_tr_b16 v[234:235], v196 offset:6656
	s_waitcnt lgkmcnt(12)
	v_mfma_f32_32x32x16_bf16 v[80:95], v[236:239], v[102:105], v[80:95]
	v_mfma_f32_32x32x16_bf16 v[64:79], v[240:243], v[102:105], v[64:79]
	ds_read_b64_tr_b16 v[236:237], v196 offset:8704
	ds_read_b64_tr_b16 v[238:239], v196 offset:10752
	s_waitcnt lgkmcnt(12)
	v_mfma_f32_32x32x16_bf16 v[0:15], v[166:169], v[150:153], v[0:15]
	ds_read_b64_tr_b16 v[240:241], v196 offset:12800
	ds_read_b64_tr_b16 v[242:243], v196 offset:14848
	s_waitcnt lgkmcnt(12)
	v_mfma_f32_32x32x16_bf16 v[0:15], v[170:173], v[154:157], v[0:15]
	ds_read_b64_tr_b16 v[150:151], v196 offset:1024
	ds_read_b64_tr_b16 v[152:153], v196 offset:3072
	s_waitcnt lgkmcnt(12)
	v_mfma_f32_32x32x16_bf16 v[0:15], v[176:179], v[158:161], v[0:15]
	ds_read_b64_tr_b16 v[154:155], v196 offset:5120
	ds_read_b64_tr_b16 v[156:157], v196 offset:7168
	s_waitcnt lgkmcnt(12)
	v_mfma_f32_32x32x16_bf16 v[0:15], v[180:183], v[162:165], v[0:15]
	ds_read_b64_tr_b16 v[158:159], v196 offset:9216
	ds_read_b64_tr_b16 v[160:161], v196 offset:11264
	s_waitcnt lgkmcnt(12)
	v_mfma_f32_32x32x16_bf16 v[48:63], v[166:169], v[228:231], v[48:63]
	ds_read_b64_tr_b16 v[162:163], v196 offset:13312
	ds_read_b64_tr_b16 v[164:165], v196 offset:15360
	s_waitcnt lgkmcnt(12)
	v_mfma_f32_32x32x16_bf16 v[48:63], v[170:173], v[232:235], v[48:63]
	ds_read_b64_tr_b16 v[228:229], v196 offset:1536
	ds_read_b64_tr_b16 v[230:231], v196 offset:3584
	s_waitcnt lgkmcnt(12)
	v_mfma_f32_32x32x16_bf16 v[48:63], v[176:179], v[236:239], v[48:63]
	ds_read_b64_tr_b16 v[232:233], v196 offset:5632
	ds_read_b64_tr_b16 v[234:235], v196 offset:7680
	s_waitcnt lgkmcnt(12)
	v_mfma_f32_32x32x16_bf16 v[48:63], v[180:183], v[240:243], v[48:63]
	ds_read_b64_tr_b16 v[236:237], v196 offset:9728
	ds_read_b64_tr_b16 v[238:239], v196 offset:11776
	s_waitcnt lgkmcnt(12)
	v_mfma_f32_32x32x16_bf16 v[32:47], v[166:169], v[150:153], v[32:47]
	ds_read_b64_tr_b16 v[240:241], v196 offset:13824
	ds_read_b64_tr_b16 v[242:243], v196 offset:15872
	s_waitcnt lgkmcnt(12)
	v_mfma_f32_32x32x16_bf16 v[32:47], v[170:173], v[154:157], v[32:47]
	s_waitcnt lgkmcnt(10)
	v_mfma_f32_32x32x16_bf16 v[32:47], v[176:179], v[158:161], v[32:47]
	s_waitcnt lgkmcnt(8)
	v_mfma_f32_32x32x16_bf16 v[32:47], v[180:183], v[162:165], v[32:47]
	s_waitcnt lgkmcnt(6)
	v_mfma_f32_32x32x16_bf16 v[16:31], v[166:169], v[228:231], v[16:31]
	s_waitcnt lgkmcnt(4)
	v_mfma_f32_32x32x16_bf16 v[16:31], v[170:173], v[232:235], v[16:31]
	s_waitcnt lgkmcnt(2)
	v_mfma_f32_32x32x16_bf16 v[16:31], v[176:179], v[236:239], v[16:31]
	s_waitcnt lgkmcnt(0)
	v_mfma_f32_32x32x16_bf16 v[16:31], v[180:183], v[240:243], v[16:31]
	s_setprio 0
	s_barrier
; __device__ __forceinline__ void partialSM(f32x16& p0, f32x16& p1, float& m_reg, float& mn, float& alpha) {
;     ...
;   float mnC = -mn * C;
; #pragma unroll
;   for (int r = 0; r < 16; ++r) p0[r] = fmaf(p0[r], C, mnC);
; #pragma unroll
;   for (int r = 0; r < 16; ++r) p1[r] = fmaf(p1[r], C, mnC);
; #pragma unroll
;   for (int r = 0; r < 16; ++r) p0[r] = __builtin_amdgcn_exp2f(p0[r]);
; }
; __device__ __forceinline__ void finishSM(f32x16& p0, f32x16& p1, float alpha, float& l_reg, bf16x8& pa0, bf16x8& pa1, bf16x8& pa2, bf16x8& pa3) {
; #pragma unroll
;   for (int r = 0; r < 16; ++r) p1[r] = __builtin_amdgcn_exp2f(p1[r]);
;   float ps = 0;
; #pragma unroll
;   for (int r = 0; r < 16; ++r) ps += p0[r];
; #pragma unroll
;   for (int r = 0; r < 16; ++r) ps += p1[r];
	v_fma_f32 v80, v80, s92, v214
	v_fma_f32 v81, v81, s92, v214
	v_fma_f32 v82, v82, s92, v214
	v_fma_f32 v83, v83, s92, v214
	v_fma_f32 v84, v84, s92, v214
	v_fma_f32 v85, v85, s92, v214
	v_fma_f32 v86, v86, s92, v214
	v_fma_f32 v87, v87, s92, v214
	v_fma_f32 v88, v88, s92, v214
	v_fma_f32 v89, v89, s92, v214
	v_fma_f32 v90, v90, s92, v214
	v_fma_f32 v91, v91, s92, v214
	v_fma_f32 v92, v92, s92, v214
	v_fma_f32 v93, v93, s92, v214
	v_fma_f32 v94, v94, s92, v214
	v_fma_f32 v95, v95, s92, v214
	v_fma_f32 v64, v64, s92, v214
	v_fma_f32 v65, v65, s92, v214
	v_fma_f32 v66, v66, s92, v214
	v_fma_f32 v67, v67, s92, v214
	v_fma_f32 v68, v68, s92, v214
	v_fma_f32 v69, v69, s92, v214
	v_fma_f32 v70, v70, s92, v214
	v_fma_f32 v71, v71, s92, v214
	v_fma_f32 v72, v72, s92, v214
	v_fma_f32 v73, v73, s92, v214
	v_fma_f32 v74, v74, s92, v214
	v_fma_f32 v75, v75, s92, v214
	v_fma_f32 v76, v76, s92, v214
	v_fma_f32 v77, v77, s92, v214
	v_fma_f32 v78, v78, s92, v214
	v_fma_f32 v79, v79, s92, v214
	v_exp_f32_e32 v80, v80
	v_exp_f32_e32 v81, v81
	v_exp_f32_e32 v82, v82
	v_exp_f32_e32 v83, v83
	v_exp_f32_e32 v84, v84
	v_exp_f32_e32 v85, v85
	v_exp_f32_e32 v86, v86
	v_exp_f32_e32 v87, v87
	v_exp_f32_e32 v88, v88
	v_exp_f32_e32 v89, v89
	v_exp_f32_e32 v90, v90
	v_exp_f32_e32 v91, v91
	v_exp_f32_e32 v92, v92
	v_exp_f32_e32 v93, v93
	v_exp_f32_e32 v94, v94
	v_exp_f32_e32 v95, v95
	v_exp_f32_e32 v64, v64
	v_exp_f32_e32 v65, v65
	v_exp_f32_e32 v66, v66
	v_exp_f32_e32 v67, v67
	v_exp_f32_e32 v68, v68
	v_exp_f32_e32 v69, v69
	v_exp_f32_e32 v70, v70
	v_exp_f32_e32 v71, v71
	v_exp_f32_e32 v72, v72
	v_exp_f32_e32 v73, v73
	v_exp_f32_e32 v74, v74
	v_exp_f32_e32 v75, v75
	v_exp_f32_e32 v76, v76
	v_exp_f32_e32 v77, v77
	v_exp_f32_e32 v78, v78
	v_exp_f32_e32 v79, v79
	v_add_f32_e32 v190, v80, v81
	v_add_f32_e32 v191, v82, v83
	v_add_f32_e32 v190, v190, v84
	v_add_f32_e32 v191, v191, v85
	v_add_f32_e32 v190, v190, v86
	v_add_f32_e32 v191, v191, v87
	v_add_f32_e32 v190, v190, v88
	v_add_f32_e32 v191, v191, v89
	v_add_f32_e32 v190, v190, v90
	v_add_f32_e32 v191, v191, v91
	v_add_f32_e32 v190, v190, v92
	v_add_f32_e32 v191, v191, v93
	v_add_f32_e32 v190, v190, v94
	v_add_f32_e32 v191, v191, v95
	v_add_f32_e32 v190, v190, v64
	v_add_f32_e32 v191, v191, v65
	v_add_f32_e32 v190, v190, v66
	v_add_f32_e32 v191, v191, v67
	v_add_f32_e32 v190, v190, v68
	v_add_f32_e32 v191, v191, v69
	v_add_f32_e32 v190, v190, v70
	v_add_f32_e32 v191, v191, v71
	v_add_f32_e32 v190, v190, v72
	v_add_f32_e32 v191, v191, v73
	v_add_f32_e32 v190, v190, v74
	v_add_f32_e32 v191, v191, v75
	v_add_f32_e32 v190, v190, v76
	v_add_f32_e32 v191, v191, v77
	v_add_f32_e32 v190, v190, v78
	v_add_f32_e32 v191, v191, v79
	v_add_f32_e32 v190, v190, v191
	v_cmp_ge_f32_e32 vcc, 0x453a4f54, v190
	s_nop 0
	s_cmp_eq_u64 vcc, exec
	s_cbranch_scc1 .Lda_pack_1
; __device__ __forceinline__ void partialSM(f32x16& p0, f32x16& p1, float& m_reg, float& mn, float& alpha) {
;   constexpr float C = SCALE * 1.4426950408889634f;
;   float pmax = p0[0];
; #pragma unroll
;   for (int r = 1; r < 16; ++r) pmax = fmaxf(pmax, p0[r]);
; #pragma unroll
;   for (int r = 0; r < 16; ++r) pmax = fmaxf(pmax, p1[r]);
;   { auto rr = __builtin_amdgcn_permlane32_swap(__float_as_uint(pmax), __float_as_uint(pmax), false, false);
;     pmax = fmaxf(__uint_as_float(rr[0]), __uint_as_float(rr[1])); }
;   if (__builtin_expect(__all(pmax - m_reg <= THR / SCALE), 1)) { mn = m_reg; alpha = 1.f; }
;   else { mn = fmaxf(m_reg, pmax); alpha = __builtin_amdgcn_exp2f((m_reg - mn) * C); m_reg = mn; }
; __device__ __forceinline__ void qkt(f32x16& p0, f32x16& p1, const bf16_t* Ks, const bf16x8* qr, int r32, int hi) {
;   p0 = f32x16{}; p1 = f32x16{};
; #pragma unroll
;   for (int d0 = 0; d0 < 8; ++d0) { int cb = (d0 * 16 + hi * 8) * 2;
;     bf16x8 b0 = *reinterpret_cast<const bf16x8*>((const char*)Ks + KSWZ(r32, cb));
;     bf16x8 b1 = *reinterpret_cast<const bf16x8*>((const char*)Ks + KSWZ(32 + r32, cb));
;     p0 = __builtin_amdgcn_mfma_f32_32x32x16_bf16(b0, qr[d0], p0, 0, 0, 0);
;     p1 = __builtin_amdgcn_mfma_f32_32x32x16_bf16(b1, qr[d0], p1, 0, 0, 0); }
; }
	ds_read_b128 v[150:153], v204 offset:16384
	ds_read_b128 v[154:157], v204 offset:24576
	ds_read_b128 v[158:161], v205 offset:16384
	ds_read_b128 v[162:165], v205 offset:24576
	ds_read_b128 v[228:231], v206 offset:16384
	ds_read_b128 v[232:235], v206 offset:24576
	ds_read_b128 v[236:239], v207 offset:16384
	ds_read_b128 v[240:243], v207 offset:24576
	s_waitcnt lgkmcnt(6)
	v_mfma_f32_32x32x16_bf16 v[80:95], v[150:153], v[130:133], 0
	v_mfma_f32_32x32x16_bf16 v[64:79], v[154:157], v[130:133], 0
	ds_read_b128 v[150:153], v208 offset:16384
	ds_read_b128 v[154:157], v208 offset:24576
	s_waitcnt lgkmcnt(6)
	v_mfma_f32_32x32x16_bf16 v[80:95], v[158:161], v[126:129], v[80:95]
	v_mfma_f32_32x32x16_bf16 v[64:79], v[162:165], v[126:129], v[64:79]
	ds_read_b128 v[158:161], v209 offset:16384
	ds_read_b128 v[162:165], v209 offset:24576
	s_waitcnt lgkmcnt(6)
	v_mfma_f32_32x32x16_bf16 v[80:95], v[228:231], v[122:125], v[80:95]
	v_mfma_f32_32x32x16_bf16 v[64:79], v[232:235], v[122:125], v[64:79]
	ds_read_b128 v[228:231], v210 offset:16384
	ds_read_b128 v[232:235], v210 offset:24576
	s_waitcnt lgkmcnt(6)
	v_mfma_f32_32x32x16_bf16 v[80:95], v[236:239], v[118:121], v[80:95]
	v_mfma_f32_32x32x16_bf16 v[64:79], v[240:243], v[118:121], v[64:79]
	ds_read_b128 v[236:239], v211 offset:16384
	ds_read_b128 v[240:243], v211 offset:24576
	s_waitcnt lgkmcnt(6)
	v_mfma_f32_32x32x16_bf16 v[80:95], v[150:153], v[114:117], v[80:95]
	v_mfma_f32_32x32x16_bf16 v[64:79], v[154:157], v[114:117], v[64:79]
	s_waitcnt lgkmcnt(4)
	v_mfma_f32_32x32x16_bf16 v[80:95], v[158:161], v[110:113], v[80:95]
	v_mfma_f32_32x32x16_bf16 v[64:79], v[162:165], v[110:113], v[64:79]
	s_waitcnt lgkmcnt(2)
	v_mfma_f32_32x32x16_bf16 v[80:95], v[228:231], v[106:109], v[80:95]
	v_mfma_f32_32x32x16_bf16 v[64:79], v[232:235], v[106:109], v[64:79]
	s_waitcnt lgkmcnt(0)
	v_mfma_f32_32x32x16_bf16 v[80:95], v[236:239], v[102:105], v[80:95]
	v_mfma_f32_32x32x16_bf16 v[64:79], v[240:243], v[102:105], v[64:79]
	s_nop 12
	v_max3_f32 v190, v80, v81, v82
	v_max3_f32 v191, v64, v65, v66
	v_max3_f32 v190, v190, v83, v84
	v_max3_f32 v191, v191, v67, v68
	v_max3_f32 v190, v190, v85, v86
	v_max3_f32 v191, v191, v69, v70
	v_max3_f32 v190, v190, v87, v88
	v_max3_f32 v191, v191, v71, v72
	v_max3_f32 v190, v190, v89, v90
	v_max3_f32 v191, v191, v73, v74
	v_max3_f32 v190, v190, v91, v92
	v_max3_f32 v191, v191, v75, v76
	v_max3_f32 v190, v190, v93, v94
	v_max3_f32 v191, v191, v77, v78
	v_max3_f32 v190, v190, v95, v79
	v_max_f32_e32 v190, v190, v191
	v_mov_b32_e32 v191, v190
	s_nop 1
	v_permlane32_swap_b32_e32 v190, v191
	s_nop 0
	v_max_f32_e32 v212, v190, v191
	v_sub_f32_e32 v215, v212, v174
	v_cmp_ge_f32_e32 vcc, s86, v215
	s_nop 0
	s_cmp_eq_u64 vcc, exec
	s_cbranch_scc1 .Lda_slow2_1
	v_max_f32_e32 v191, v174, v212
	v_sub_f32_e32 v215, v174, v191
	v_mul_f32_e32 v215, s92, v215
	v_exp_f32_e32 v213, v215
	v_mov_b32_e32 v174, v191
	v_mul_f32_e32 v214, 0xbe0293ee, v174
	v_mul_f32_e32 v175, v175, v213
	s_and_saveexec_b64 s[12:13], s[40:41]
	ds_write_b32 v199, v213 offset:128
	s_or_b64 exec, exec, s[12:13]
	s_waitcnt lgkmcnt(0)
	v_add_u32_e32 v215, v99, v96
	ds_read_b128 v[228:231], v215 offset:128
	ds_read_b128 v[232:235], v215 offset:160
	ds_read_b128 v[236:239], v215 offset:192
	ds_read_b128 v[240:243], v215 offset:224
	s_waitcnt lgkmcnt(0)
	v_pk_mul_f32 v[0:1], v[0:1], v[228:229]
	v_pk_mul_f32 v[2:3], v[2:3], v[230:231]
	v_pk_mul_f32 v[4:5], v[4:5], v[232:233]
	v_pk_mul_f32 v[6:7], v[6:7], v[234:235]
	v_pk_mul_f32 v[8:9], v[8:9], v[236:237]
	v_pk_mul_f32 v[10:11], v[10:11], v[238:239]
	v_pk_mul_f32 v[12:13], v[12:13], v[240:241]
	v_pk_mul_f32 v[14:15], v[14:15], v[242:243]
	v_pk_mul_f32 v[48:49], v[48:49], v[228:229]
	v_pk_mul_f32 v[50:51], v[50:51], v[230:231]
	v_pk_mul_f32 v[52:53], v[52:53], v[232:233]
	v_pk_mul_f32 v[54:55], v[54:55], v[234:235]
	v_pk_mul_f32 v[56:57], v[56:57], v[236:237]
	v_pk_mul_f32 v[58:59], v[58:59], v[238:239]
	v_pk_mul_f32 v[60:61], v[60:61], v[240:241]
	v_pk_mul_f32 v[62:63], v[62:63], v[242:243]
	v_pk_mul_f32 v[32:33], v[32:33], v[228:229]
	v_pk_mul_f32 v[34:35], v[34:35], v[230:231]
	v_pk_mul_f32 v[36:37], v[36:37], v[232:233]
	v_pk_mul_f32 v[38:39], v[38:39], v[234:235]
	v_pk_mul_f32 v[40:41], v[40:41], v[236:237]
	v_pk_mul_f32 v[42:43], v[42:43], v[238:239]
	v_pk_mul_f32 v[44:45], v[44:45], v[240:241]
	v_pk_mul_f32 v[46:47], v[46:47], v[242:243]
	v_pk_mul_f32 v[16:17], v[16:17], v[228:229]
	v_pk_mul_f32 v[18:19], v[18:19], v[230:231]
	v_pk_mul_f32 v[20:21], v[20:21], v[232:233]
	v_pk_mul_f32 v[22:23], v[22:23], v[234:235]
	v_pk_mul_f32 v[24:25], v[24:25], v[236:237]
	v_pk_mul_f32 v[26:27], v[26:27], v[238:239]
	v_pk_mul_f32 v[28:29], v[28:29], v[240:241]
	v_pk_mul_f32 v[30:31], v[30:31], v[242:243]

; #define SBAR() __builtin_amdgcn_sched_barrier(0)
; __device__ __forceinline__ void finishSM(f32x16& p0, f32x16& p1, float alpha, float& l_reg, bf16x8& pa0, bf16x8& pa1, bf16x8& pa2, bf16x8& pa3) {
;     ...
;   l_reg = l_reg * alpha + ps;
;     ...
;   PK4(p0, 0, pa0); PK4(p0, 8, pa1); PK4(p1, 0, pa2); PK4(p1, 8, pa3);
; __device__ __forceinline__ void qkt(f32x16& p0, f32x16& p1, const bf16_t* Ks, const bf16x8* qr, int r32, int hi) {
;   p0 = f32x16{}; p1 = f32x16{};
; #pragma unroll
;   for (int d0 = 0; d0 < 8; ++d0) { int cb = (d0 * 16 + hi * 8) * 2;
;     bf16x8 b0 = *reinterpret_cast<const bf16x8*>((const char*)Ks + KSWZ(r32, cb));
;     bf16x8 b1 = *reinterpret_cast<const bf16x8*>((const char*)Ks + KSWZ(32 + r32, cb));
;     p0 = __builtin_amdgcn_mfma_f32_32x32x16_bf16(b0, qr[d0], p0, 0, 0, 0);
;     p1 = __builtin_amdgcn_mfma_f32_32x32x16_bf16(b1, qr[d0], p1, 0, 0, 0); }
; }
; __device__ __forceinline__ int v_st(int k, int c) { const int kk = (k & ~0xC) | ((k & 4) << 1) | ((k & 8) >> 1); return ((kk >> 3) * 4 + (c >> 5)) * 512 + ((kk & 7) * 32 + (c & 31)) * 2; }
; __device__ __forceinline__ int v_rd_base(int lane) { return ((lane & 3) << 3) | (((lane >> 2) & 3) << 6) | (((lane >> 4) & 1) << 5) | (((lane >> 5) & 1) << 8); }
; template <int OFF> __device__ __forceinline__ s16x4 tr_read(int vb) {
;   s16x4 r; asm volatile("ds_read_b64_tr_b16 %0, %1 offset:%2" : "=&v"(r) : "v"(vb), "i"(OFF) : "memory"); return r;
; }
; template <int D0> __device__ __forceinline__ void pv_one(f32x16& od, int vb, bf16x8 pa0, bf16x8 pa1, bf16x8 pa2, bf16x8 pa3) {
;   const s16x4 l0 = tr_read<v_rd_off(D0, 0, 0)>(vb), h0 = tr_read<v_rd_off(D0, 0, 1)>(vb), l1 = tr_read<v_rd_off(D0, 1, 0)>(vb), h1 = tr_read<v_rd_off(D0, 1, 1)>(vb);
;   const s16x4 l2 = tr_read<v_rd_off(D0, 2, 0)>(vb), h2 = tr_read<v_rd_off(D0, 2, 1)>(vb), l3 = tr_read<v_rd_off(D0, 3, 0)>(vb), h3 = tr_read<v_rd_off(D0, 3, 1)>(vb);
;   asm volatile("s_waitcnt lgkmcnt(0)" ::: "memory"); SBAR();
;     ...
;   od = __builtin_amdgcn_mfma_f32_32x32x16_bf16(pa0, PK(l0, h0), od, 0, 0, 0);
;   od = __builtin_amdgcn_mfma_f32_32x32x16_bf16(pa1, PK(l1, h1), od, 0, 0, 0);
;   od = __builtin_amdgcn_mfma_f32_32x32x16_bf16(pa2, PK(l2, h2), od, 0, 0, 0);
;   od = __builtin_amdgcn_mfma_f32_32x32x16_bf16(pa3, PK(l3, h3), od, 0, 0, 0);
;     ...
; }
; __device__ __forceinline__ void pv_d0(f32x16* o, int vb, bf16x8 pa0, bf16x8 pa1, bf16x8 pa2, bf16x8 pa3) {
.Lda_pack_1:
	v_add_f32_e32 v175, v175, v190
	v_cvt_pk_bf16_f32 v166, v80, v81
	v_cvt_pk_bf16_f32 v167, v82, v83
	v_cvt_pk_bf16_f32 v168, v84, v85
	v_cvt_pk_bf16_f32 v169, v86, v87
	v_cvt_pk_bf16_f32 v170, v88, v89
	v_cvt_pk_bf16_f32 v171, v90, v91
	v_cvt_pk_bf16_f32 v172, v92, v93
	v_cvt_pk_bf16_f32 v173, v94, v95
	v_cvt_pk_bf16_f32 v176, v64, v65
	v_cvt_pk_bf16_f32 v177, v66, v67
	v_cvt_pk_bf16_f32 v178, v68, v69
	v_cvt_pk_bf16_f32 v179, v70, v71
	v_cvt_pk_bf16_f32 v180, v72, v73
	v_cvt_pk_bf16_f32 v181, v74, v75
	v_cvt_pk_bf16_f32 v182, v76, v77
	v_cvt_pk_bf16_f32 v183, v78, v79
	v_permlane32_swap_b32_e32 v166, v168
	v_permlane32_swap_b32_e32 v167, v169
	v_permlane32_swap_b32_e32 v170, v172
	v_permlane32_swap_b32_e32 v171, v173
	v_permlane32_swap_b32_e32 v176, v178
	v_permlane32_swap_b32_e32 v177, v179
	v_permlane32_swap_b32_e32 v180, v182
	v_permlane32_swap_b32_e32 v181, v183
	s_add_u32 s31, s31, 1
	s_cmp_lt_u32 s31, 132
	s_cbranch_scc0 .Lda_skipk_1
	ds_read_b128 v[150:153], v204 offset:32768
	ds_read_b128 v[154:157], v204 offset:40960
	ds_read_b128 v[158:161], v205 offset:32768
	ds_read_b128 v[162:165], v205 offset:40960
	ds_read_b128 v[228:231], v206 offset:32768
	ds_read_b128 v[232:235], v206 offset:40960
	ds_read_b128 v[236:239], v207 offset:32768
	ds_read_b128 v[240:243], v207 offset:40960
.Lda_skipk_1:
	s_barrier
	s_setprio 3
	s_waitcnt vmcnt(4)
	ds_write_b128 v197, v[134:137] offset:0
	ds_write_b128 v197, v[138:141] offset:8192
	ds_write_b128 v185, v[142:145] offset:0
	ds_write_b128 v185, v[146:149] offset:8192
	s_waitcnt lgkmcnt(10)
	v_mfma_f32_32x32x16_bf16 v[80:95], v[150:153], v[130:133], 0
	v_mfma_f32_32x32x16_bf16 v[64:79], v[154:157], v[130:133], 0
	global_load_dwordx4 v[134:137], v184, s[16:17]
	global_load_dwordx4 v[138:141], v184, s[2:3]
	global_load_dwordx4 v[142:145], v184, s[14:15]
	global_load_dwordx4 v[146:149], v184, s[10:11]
	s_add_u32 s16, s16, 0x60000
	s_addc_u32 s17, s17, 0
	s_add_u32 s2, s2, 0x60000
	s_addc_u32 s3, s3, 0
	s_add_u32 s14, s14, 0x60000
	s_addc_u32 s15, s15, 0
	s_add_u32 s10, s10, 0x60000
	s_addc_u32 s11, s11, 0
	ds_read_b128 v[150:153], v208 offset:32768
	ds_read_b128 v[154:157], v208 offset:40960
	s_waitcnt lgkmcnt(10)
	v_mfma_f32_32x32x16_bf16 v[80:95], v[158:161], v[126:129], v[80:95]
	v_mfma_f32_32x32x16_bf16 v[64:79], v[162:165], v[126:129], v[64:79]
	ds_read_b128 v[158:161], v209 offset:32768
	ds_read_b128 v[162:165], v209 offset:40960
	s_waitcnt lgkmcnt(10)
	v_mfma_f32_32x32x16_bf16 v[80:95], v[228:231], v[122:125], v[80:95]
	v_mfma_f32_32x32x16_bf16 v[64:79], v[232:235], v[122:125], v[64:79]
	ds_read_b128 v[228:231], v210 offset:32768
	ds_read_b128 v[232:235], v210 offset:40960
	s_waitcnt lgkmcnt(10)
	v_mfma_f32_32x32x16_bf16 v[80:95], v[236:239], v[118:121], v[80:95]
	v_mfma_f32_32x32x16_bf16 v[64:79], v[240:243], v[118:121], v[64:79]
	ds_read_b128 v[236:239], v211 offset:32768
	ds_read_b128 v[240:243], v211 offset:40960
	s_waitcnt lgkmcnt(6)
	v_mfma_f32_32x32x16_bf16 v[80:95], v[150:153], v[114:117], v[80:95]
	v_mfma_f32_32x32x16_bf16 v[64:79], v[154:157], v[114:117], v[64:79]
	ds_read_b64_tr_b16 v[150:151], v196 offset:16384
	ds_read_b64_tr_b16 v[152:153], v196 offset:18432
	ds_read_b64_tr_b16 v[154:155], v196 offset:20480
	ds_read_b64_tr_b16 v[156:157], v196 offset:22528
	s_waitcnt lgkmcnt(8)
	v_mfma_f32_32x32x16_bf16 v[80:95], v[158:161], v[110:113], v[80:95]
	v_mfma_f32_32x32x16_bf16 v[64:79], v[162:165], v[110:113], v[64:79]
	ds_read_b64_tr_b16 v[158:159], v196 offset:24576
	ds_read_b64_tr_b16 v[160:161], v196 offset:26624
	ds_read_b64_tr_b16 v[162:163], v196 offset:28672
	ds_read_b64_tr_b16 v[164:165], v196 offset:30720
	s_waitcnt lgkmcnt(10)
	v_mfma_f32_32x32x16_bf16 v[80:95], v[228:231], v[106:109], v[80:95]
	v_mfma_f32_32x32x16_bf16 v[64:79], v[232:235], v[106:109], v[64:79]
	ds_read_b64_tr_b16 v[228:229], v196 offset:16896
	ds_read_b64_tr_b16 v[230:231], v196 offset:18944
	ds_read_b64_tr_b16 v[232:233], v196 offset:20992
	ds_read_b64_tr_b16 v[234:235], v196 offset:23040
	s_waitcnt lgkmcnt(12)
	v_mfma_f32_32x32x16_bf16 v[80:95], v[236:239], v[102:105], v[80:95]
	v_mfma_f32_32x32x16_bf16 v[64:79], v[240:243], v[102:105], v[64:79]
	ds_read_b64_tr_b16 v[236:237], v196 offset:25088
	ds_read_b64_tr_b16 v[238:239], v196 offset:27136
	s_waitcnt lgkmcnt(12)
	v_mfma_f32_32x32x16_bf16 v[0:15], v[166:169], v[150:153], v[0:15]
	ds_read_b64_tr_b16 v[240:241], v196 offset:29184
	ds_read_b64_tr_b16 v[242:243], v196 offset:31232
	s_waitcnt lgkmcnt(12)
	v_mfma_f32_32x32x16_bf16 v[0:15], v[170:173], v[154:157], v[0:15]
	ds_read_b64_tr_b16 v[150:151], v196 offset:17408
	ds_read_b64_tr_b16 v[152:153], v196 offset:19456
	s_waitcnt lgkmcnt(12)
	v_mfma_f32_32x32x16_bf16 v[0:15], v[176:179], v[158:161], v[0:15]
	ds_read_b64_tr_b16 v[154:155], v196 offset:21504
	ds_read_b64_tr_b16 v[156:157], v196 offset:23552
	s_waitcnt lgkmcnt(12)
	v_mfma_f32_32x32x16_bf16 v[0:15], v[180:183], v[162:165], v[0:15]
	ds_read_b64_tr_b16 v[158:159], v196 offset:25600
	ds_read_b64_tr_b16 v[160:161], v196 offset:27648
	s_waitcnt lgkmcnt(12)
	v_mfma_f32_32x32x16_bf16 v[48:63], v[166:169], v[228:231], v[48:63]
	ds_read_b64_tr_b16 v[162:163], v196 offset:29696
	ds_read_b64_tr_b16 v[164:165], v196 offset:31744
	s_waitcnt lgkmcnt(12)
	v_mfma_f32_32x32x16_bf16 v[48:63], v[170:173], v[232:235], v[48:63]
	ds_read_b64_tr_b16 v[228:229], v196 offset:17920
	ds_read_b64_tr_b16 v[230:231], v196 offset:19968
	s_waitcnt lgkmcnt(12)
	v_mfma_f32_32x32x16_bf16 v[48:63], v[176:179], v[236:239], v[48:63]
	ds_read_b64_tr_b16 v[232:233], v196 offset:22016
	ds_read_b64_tr_b16 v[234:235], v196 offset:24064
	s_waitcnt lgkmcnt(12)
	v_mfma_f32_32x32x16_bf16 v[48:63], v[180:183], v[240:243], v[48:63]
	ds_read_b64_tr_b16 v[236:237], v196 offset:26112
	ds_read_b64_tr_b16 v[238:239], v196 offset:28160
	s_waitcnt lgkmcnt(12)
	v_mfma_f32_32x32x16_bf16 v[32:47], v[166:169], v[150:153], v[32:47]
	ds_read_b64_tr_b16 v[240:241], v196 offset:30208
	ds_read_b64_tr_b16 v[242:243], v196 offset:32256
	s_waitcnt lgkmcnt(12)
	v_mfma_f32_32x32x16_bf16 v[32:47], v[170:173], v[154:157], v[32:47]
	s_waitcnt lgkmcnt(10)
	v_mfma_f32_32x32x16_bf16 v[32:47], v[176:179], v[158:161], v[32:47]
	s_waitcnt lgkmcnt(8)
	v_mfma_f32_32x32x16_bf16 v[32:47], v[180:183], v[162:165], v[32:47]
	s_waitcnt lgkmcnt(6)
	v_mfma_f32_32x32x16_bf16 v[16:31], v[166:169], v[228:231], v[16:31]
	s_waitcnt lgkmcnt(4)
	v_mfma_f32_32x32x16_bf16 v[16:31], v[170:173], v[232:235], v[16:31]
	s_waitcnt lgkmcnt(2)
	v_mfma_f32_32x32x16_bf16 v[16:31], v[176:179], v[236:239], v[16:31]
	s_waitcnt lgkmcnt(0)
	v_mfma_f32_32x32x16_bf16 v[16:31], v[180:183], v[240:243], v[16:31]
	s_setprio 0
	s_barrier
; __device__ __forceinline__ void partialSM(f32x16& p0, f32x16& p1, float& m_reg, float& mn, float& alpha) {
;     ...
;   float mnC = -mn * C;
; #pragma unroll
;   for (int r = 0; r < 16; ++r) p0[r] = fmaf(p0[r], C, mnC);
; #pragma unroll
;   for (int r = 0; r < 16; ++r) p1[r] = fmaf(p1[r], C, mnC);
; #pragma unroll
;   for (int r = 0; r < 16; ++r) p0[r] = __builtin_amdgcn_exp2f(p0[r]);
; }
; __device__ __forceinline__ void finishSM(f32x16& p0, f32x16& p1, float alpha, float& l_reg, bf16x8& pa0, bf16x8& pa1, bf16x8& pa2, bf16x8& pa3) {
; #pragma unroll
;   for (int r = 0; r < 16; ++r) p1[r] = __builtin_amdgcn_exp2f(p1[r]);
;   float ps = 0;
; #pragma unroll
;   for (int r = 0; r < 16; ++r) ps += p0[r];
; #pragma unroll
;   for (int r = 0; r < 16; ++r) ps += p1[r];
	v_fma_f32 v80, v80, s92, v214
	v_fma_f32 v81, v81, s92, v214
	v_fma_f32 v82, v82, s92, v214
	v_fma_f32 v83, v83, s92, v214
	v_fma_f32 v84, v84, s92, v214
	v_fma_f32 v85, v85, s92, v214
	v_fma_f32 v86, v86, s92, v214
	v_fma_f32 v87, v87, s92, v214
	v_fma_f32 v88, v88, s92, v214
	v_fma_f32 v89, v89, s92, v214
	v_fma_f32 v90, v90, s92, v214
	v_fma_f32 v91, v91, s92, v214
	v_fma_f32 v92, v92, s92, v214
	v_fma_f32 v93, v93, s92, v214
	v_fma_f32 v94, v94, s92, v214
	v_fma_f32 v95, v95, s92, v214
	v_fma_f32 v64, v64, s92, v214
	v_fma_f32 v65, v65, s92, v214
	v_fma_f32 v66, v66, s92, v214
	v_fma_f32 v67, v67, s92, v214
	v_fma_f32 v68, v68, s92, v214
	v_fma_f32 v69, v69, s92, v214
	v_fma_f32 v70, v70, s92, v214
	v_fma_f32 v71, v71, s92, v214
	v_fma_f32 v72, v72, s92, v214
	v_fma_f32 v73, v73, s92, v214
	v_fma_f32 v74, v74, s92, v214
	v_fma_f32 v75, v75, s92, v214
	v_fma_f32 v76, v76, s92, v214
	v_fma_f32 v77, v77, s92, v214
	v_fma_f32 v78, v78, s92, v214
	v_fma_f32 v79, v79, s92, v214
	v_exp_f32_e32 v80, v80
	v_exp_f32_e32 v81, v81
	v_exp_f32_e32 v82, v82
	v_exp_f32_e32 v83, v83
	v_exp_f32_e32 v84, v84
	v_exp_f32_e32 v85, v85
	v_exp_f32_e32 v86, v86
	v_exp_f32_e32 v87, v87
	v_exp_f32_e32 v88, v88
	v_exp_f32_e32 v89, v89
	v_exp_f32_e32 v90, v90
	v_exp_f32_e32 v91, v91
	v_exp_f32_e32 v92, v92
	v_exp_f32_e32 v93, v93
	v_exp_f32_e32 v94, v94
	v_exp_f32_e32 v95, v95
	v_exp_f32_e32 v64, v64
	v_exp_f32_e32 v65, v65
	v_exp_f32_e32 v66, v66
	v_exp_f32_e32 v67, v67
	v_exp_f32_e32 v68, v68
	v_exp_f32_e32 v69, v69
	v_exp_f32_e32 v70, v70
	v_exp_f32_e32 v71, v71
	v_exp_f32_e32 v72, v72
	v_exp_f32_e32 v73, v73
	v_exp_f32_e32 v74, v74
	v_exp_f32_e32 v75, v75
	v_exp_f32_e32 v76, v76
	v_exp_f32_e32 v77, v77
	v_exp_f32_e32 v78, v78
	v_exp_f32_e32 v79, v79
	v_add_f32_e32 v190, v80, v81
	v_add_f32_e32 v191, v82, v83
	v_add_f32_e32 v190, v190, v84
	v_add_f32_e32 v191, v191, v85
	v_add_f32_e32 v190, v190, v86
	v_add_f32_e32 v191, v191, v87
	v_add_f32_e32 v190, v190, v88
	v_add_f32_e32 v191, v191, v89
	v_add_f32_e32 v190, v190, v90
	v_add_f32_e32 v191, v191, v91
	v_add_f32_e32 v190, v190, v92
	v_add_f32_e32 v191, v191, v93
	v_add_f32_e32 v190, v190, v94
	v_add_f32_e32 v191, v191, v95
	v_add_f32_e32 v190, v190, v64
	v_add_f32_e32 v191, v191, v65
	v_add_f32_e32 v190, v190, v66
	v_add_f32_e32 v191, v191, v67
	v_add_f32_e32 v190, v190, v68
	v_add_f32_e32 v191, v191, v69
	v_add_f32_e32 v190, v190, v70
	v_add_f32_e32 v191, v191, v71
	v_add_f32_e32 v190, v190, v72
	v_add_f32_e32 v191, v191, v73
	v_add_f32_e32 v190, v190, v74
	v_add_f32_e32 v191, v191, v75
	v_add_f32_e32 v190, v190, v76
	v_add_f32_e32 v191, v191, v77
	v_add_f32_e32 v190, v190, v78
	v_add_f32_e32 v191, v191, v79
	v_add_f32_e32 v190, v190, v191
	v_cmp_ge_f32_e32 vcc, 0x453a4f54, v190
	s_nop 0
	s_cmp_eq_u64 vcc, exec
	s_cbranch_scc1 .Lda_pack_2
; __device__ __forceinline__ void partialSM(f32x16& p0, f32x16& p1, float& m_reg, float& mn, float& alpha) {
;   constexpr float C = SCALE * 1.4426950408889634f;
;   float pmax = p0[0];
; #pragma unroll
;   for (int r = 1; r < 16; ++r) pmax = fmaxf(pmax, p0[r]);
; #pragma unroll
;   for (int r = 0; r < 16; ++r) pmax = fmaxf(pmax, p1[r]);
;   { auto rr = __builtin_amdgcn_permlane32_swap(__float_as_uint(pmax), __float_as_uint(pmax), false, false);
;     pmax = fmaxf(__uint_as_float(rr[0]), __uint_as_float(rr[1])); }
;   if (__builtin_expect(__all(pmax - m_reg <= THR / SCALE), 1)) { mn = m_reg; alpha = 1.f; }
;   else { mn = fmaxf(m_reg, pmax); alpha = __builtin_amdgcn_exp2f((m_reg - mn) * C); m_reg = mn; }
; __device__ __forceinline__ void qkt(f32x16& p0, f32x16& p1, const bf16_t* Ks, const bf16x8* qr, int r32, int hi) {
;   p0 = f32x16{}; p1 = f32x16{};
; #pragma unroll
;   for (int d0 = 0; d0 < 8; ++d0) { int cb = (d0 * 16 + hi * 8) * 2;
;     bf16x8 b0 = *reinterpret_cast<const bf16x8*>((const char*)Ks + KSWZ(r32, cb));
;     bf16x8 b1 = *reinterpret_cast<const bf16x8*>((const char*)Ks + KSWZ(32 + r32, cb));
;     p0 = __builtin_amdgcn_mfma_f32_32x32x16_bf16(b0, qr[d0], p0, 0, 0, 0);
;     p1 = __builtin_amdgcn_mfma_f32_32x32x16_bf16(b1, qr[d0], p1, 0, 0, 0); }
; }
	ds_read_b128 v[150:153], v204 offset:32768
	ds_read_b128 v[154:157], v204 offset:40960
	ds_read_b128 v[158:161], v205 offset:32768
	ds_read_b128 v[162:165], v205 offset:40960
	ds_read_b128 v[228:231], v206 offset:32768
	ds_read_b128 v[232:235], v206 offset:40960
	ds_read_b128 v[236:239], v207 offset:32768
	ds_read_b128 v[240:243], v207 offset:40960
	s_waitcnt lgkmcnt(6)
	v_mfma_f32_32x32x16_bf16 v[80:95], v[150:153], v[130:133], 0
	v_mfma_f32_32x32x16_bf16 v[64:79], v[154:157], v[130:133], 0
	ds_read_b128 v[150:153], v208 offset:32768
	ds_read_b128 v[154:157], v208 offset:40960
	s_waitcnt lgkmcnt(6)
	v_mfma_f32_32x32x16_bf16 v[80:95], v[158:161], v[126:129], v[80:95]
	v_mfma_f32_32x32x16_bf16 v[64:79], v[162:165], v[126:129], v[64:79]
	ds_read_b128 v[158:161], v209 offset:32768
	ds_read_b128 v[162:165], v209 offset:40960
	s_waitcnt lgkmcnt(6)
	v_mfma_f32_32x32x16_bf16 v[80:95], v[228:231], v[122:125], v[80:95]
	v_mfma_f32_32x32x16_bf16 v[64:79], v[232:235], v[122:125], v[64:79]
	ds_read_b128 v[228:231], v210 offset:32768
	ds_read_b128 v[232:235], v210 offset:40960
	s_waitcnt lgkmcnt(6)
	v_mfma_f32_32x32x16_bf16 v[80:95], v[236:239], v[118:121], v[80:95]
	v_mfma_f32_32x32x16_bf16 v[64:79], v[240:243], v[118:121], v[64:79]
	ds_read_b128 v[236:239], v211 offset:32768
	ds_read_b128 v[240:243], v211 offset:40960
	s_waitcnt lgkmcnt(6)
	v_mfma_f32_32x32x16_bf16 v[80:95], v[150:153], v[114:117], v[80:95]
	v_mfma_f32_32x32x16_bf16 v[64:79], v[154:157], v[114:117], v[64:79]
	s_waitcnt lgkmcnt(4)
	v_mfma_f32_32x32x16_bf16 v[80:95], v[158:161], v[110:113], v[80:95]
	v_mfma_f32_32x32x16_bf16 v[64:79], v[162:165], v[110:113], v[64:79]
	s_waitcnt lgkmcnt(2)
	v_mfma_f32_32x32x16_bf16 v[80:95], v[228:231], v[106:109], v[80:95]
	v_mfma_f32_32x32x16_bf16 v[64:79], v[232:235], v[106:109], v[64:79]
	s_waitcnt lgkmcnt(0)
	v_mfma_f32_32x32x16_bf16 v[80:95], v[236:239], v[102:105], v[80:95]
	v_mfma_f32_32x32x16_bf16 v[64:79], v[240:243], v[102:105], v[64:79]
	s_nop 12
	v_max3_f32 v190, v80, v81, v82
	v_max3_f32 v191, v64, v65, v66
	v_max3_f32 v190, v190, v83, v84
	v_max3_f32 v191, v191, v67, v68
	v_max3_f32 v190, v190, v85, v86
	v_max3_f32 v191, v191, v69, v70
	v_max3_f32 v190, v190, v87, v88
	v_max3_f32 v191, v191, v71, v72
	v_max3_f32 v190, v190, v89, v90
	v_max3_f32 v191, v191, v73, v74
	v_max3_f32 v190, v190, v91, v92
	v_max3_f32 v191, v191, v75, v76
	v_max3_f32 v190, v190, v93, v94
	v_max3_f32 v191, v191, v77, v78
	v_max3_f32 v190, v190, v95, v79
	v_max_f32_e32 v190, v190, v191
	v_mov_b32_e32 v191, v190
	s_nop 1
	v_permlane32_swap_b32_e32 v190, v191
	s_nop 0
	v_max_f32_e32 v212, v190, v191
	v_sub_f32_e32 v215, v212, v174
	v_cmp_ge_f32_e32 vcc, s86, v215
	s_nop 0
	s_cmp_eq_u64 vcc, exec
	s_cbranch_scc1 .Lda_slow2_2
	v_max_f32_e32 v191, v174, v212
	v_sub_f32_e32 v215, v174, v191
	v_mul_f32_e32 v215, s92, v215
	v_exp_f32_e32 v213, v215
	v_mov_b32_e32 v174, v191
	v_mul_f32_e32 v214, 0xbe0293ee, v174
	v_mul_f32_e32 v175, v175, v213
	s_and_saveexec_b64 s[12:13], s[40:41]
	ds_write_b32 v199, v213 offset:128
	s_or_b64 exec, exec, s[12:13]
	s_waitcnt lgkmcnt(0)
	v_add_u32_e32 v215, v99, v96
	ds_read_b128 v[228:231], v215 offset:128
	ds_read_b128 v[232:235], v215 offset:160
	ds_read_b128 v[236:239], v215 offset:192
	ds_read_b128 v[240:243], v215 offset:224
	s_waitcnt lgkmcnt(0)
	v_pk_mul_f32 v[0:1], v[0:1], v[228:229]
	v_pk_mul_f32 v[2:3], v[2:3], v[230:231]
	v_pk_mul_f32 v[4:5], v[4:5], v[232:233]
	v_pk_mul_f32 v[6:7], v[6:7], v[234:235]
	v_pk_mul_f32 v[8:9], v[8:9], v[236:237]
	v_pk_mul_f32 v[10:11], v[10:11], v[238:239]
	v_pk_mul_f32 v[12:13], v[12:13], v[240:241]
	v_pk_mul_f32 v[14:15], v[14:15], v[242:243]
	v_pk_mul_f32 v[48:49], v[48:49], v[228:229]
	v_pk_mul_f32 v[50:51], v[50:51], v[230:231]
	v_pk_mul_f32 v[52:53], v[52:53], v[232:233]
	v_pk_mul_f32 v[54:55], v[54:55], v[234:235]
	v_pk_mul_f32 v[56:57], v[56:57], v[236:237]
	v_pk_mul_f32 v[58:59], v[58:59], v[238:239]
	v_pk_mul_f32 v[60:61], v[60:61], v[240:241]
	v_pk_mul_f32 v[62:63], v[62:63], v[242:243]
	v_pk_mul_f32 v[32:33], v[32:33], v[228:229]
	v_pk_mul_f32 v[34:35], v[34:35], v[230:231]
	v_pk_mul_f32 v[36:37], v[36:37], v[232:233]
	v_pk_mul_f32 v[38:39], v[38:39], v[234:235]
	v_pk_mul_f32 v[40:41], v[40:41], v[236:237]
	v_pk_mul_f32 v[42:43], v[42:43], v[238:239]
	v_pk_mul_f32 v[44:45], v[44:45], v[240:241]
	v_pk_mul_f32 v[46:47], v[46:47], v[242:243]
	v_pk_mul_f32 v[16:17], v[16:17], v[228:229]
	v_pk_mul_f32 v[18:19], v[18:19], v[230:231]
	v_pk_mul_f32 v[20:21], v[20:21], v[232:233]
	v_pk_mul_f32 v[22:23], v[22:23], v[234:235]
	v_pk_mul_f32 v[24:25], v[24:25], v[236:237]
	v_pk_mul_f32 v[26:27], v[26:27], v[238:239]
	v_pk_mul_f32 v[28:29], v[28:29], v[240:241]
	v_pk_mul_f32 v[30:31], v[30:31], v[242:243]

; #define SBAR() __builtin_amdgcn_sched_barrier(0)
; __device__ __forceinline__ void finishSM(f32x16& p0, f32x16& p1, float alpha, float& l_reg, bf16x8& pa0, bf16x8& pa1, bf16x8& pa2, bf16x8& pa3) {
;     ...
;   l_reg = l_reg * alpha + ps;
;     ...
;   PK4(p0, 0, pa0); PK4(p0, 8, pa1); PK4(p1, 0, pa2); PK4(p1, 8, pa3);
; __device__ __forceinline__ void qkt(f32x16& p0, f32x16& p1, const bf16_t* Ks, const bf16x8* qr, int r32, int hi) {
;   p0 = f32x16{}; p1 = f32x16{};
; #pragma unroll
;   for (int d0 = 0; d0 < 8; ++d0) { int cb = (d0 * 16 + hi * 8) * 2;
;     bf16x8 b0 = *reinterpret_cast<const bf16x8*>((const char*)Ks + KSWZ(r32, cb));
;     bf16x8 b1 = *reinterpret_cast<const bf16x8*>((const char*)Ks + KSWZ(32 + r32, cb));
;     p0 = __builtin_amdgcn_mfma_f32_32x32x16_bf16(b0, qr[d0], p0, 0, 0, 0);
;     p1 = __builtin_amdgcn_mfma_f32_32x32x16_bf16(b1, qr[d0], p1, 0, 0, 0); }
; }
; __device__ __forceinline__ int v_st(int k, int c) { const int kk = (k & ~0xC) | ((k & 4) << 1) | ((k & 8) >> 1); return ((kk >> 3) * 4 + (c >> 5)) * 512 + ((kk & 7) * 32 + (c & 31)) * 2; }
; __device__ __forceinline__ int v_rd_base(int lane) { return ((lane & 3) << 3) | (((lane >> 2) & 3) << 6) | (((lane >> 4) & 1) << 5) | (((lane >> 5) & 1) << 8); }
; template <int OFF> __device__ __forceinline__ s16x4 tr_read(int vb) {
;   s16x4 r; asm volatile("ds_read_b64_tr_b16 %0, %1 offset:%2" : "=&v"(r) : "v"(vb), "i"(OFF) : "memory"); return r;
; }
; template <int D0> __device__ __forceinline__ void pv_one(f32x16& od, int vb, bf16x8 pa0, bf16x8 pa1, bf16x8 pa2, bf16x8 pa3) {
;   const s16x4 l0 = tr_read<v_rd_off(D0, 0, 0)>(vb), h0 = tr_read<v_rd_off(D0, 0, 1)>(vb), l1 = tr_read<v_rd_off(D0, 1, 0)>(vb), h1 = tr_read<v_rd_off(D0, 1, 1)>(vb);
;   const s16x4 l2 = tr_read<v_rd_off(D0, 2, 0)>(vb), h2 = tr_read<v_rd_off(D0, 2, 1)>(vb), l3 = tr_read<v_rd_off(D0, 3, 0)>(vb), h3 = tr_read<v_rd_off(D0, 3, 1)>(vb);
;   asm volatile("s_waitcnt lgkmcnt(0)" ::: "memory"); SBAR();
;     ...
;   od = __builtin_amdgcn_mfma_f32_32x32x16_bf16(pa0, PK(l0, h0), od, 0, 0, 0);
;   od = __builtin_amdgcn_mfma_f32_32x32x16_bf16(pa1, PK(l1, h1), od, 0, 0, 0);
;   od = __builtin_amdgcn_mfma_f32_32x32x16_bf16(pa2, PK(l2, h2), od, 0, 0, 0);
;   od = __builtin_amdgcn_mfma_f32_32x32x16_bf16(pa3, PK(l3, h3), od, 0, 0, 0);
;     ...
; }
; __device__ __forceinline__ void pv_d0(f32x16* o, int vb, bf16x8 pa0, bf16x8 pa1, bf16x8 pa2, bf16x8 pa3) {
.Lda_pack_2:
	v_add_f32_e32 v175, v175, v190
	v_cvt_pk_bf16_f32 v166, v80, v81
	v_cvt_pk_bf16_f32 v167, v82, v83
	v_cvt_pk_bf16_f32 v168, v84, v85
	v_cvt_pk_bf16_f32 v169, v86, v87
	v_cvt_pk_bf16_f32 v170, v88, v89
	v_cvt_pk_bf16_f32 v171, v90, v91
	v_cvt_pk_bf16_f32 v172, v92, v93
	v_cvt_pk_bf16_f32 v173, v94, v95
	v_cvt_pk_bf16_f32 v176, v64, v65
	v_cvt_pk_bf16_f32 v177, v66, v67
	v_cvt_pk_bf16_f32 v178, v68, v69
	v_cvt_pk_bf16_f32 v179, v70, v71
	v_cvt_pk_bf16_f32 v180, v72, v73
	v_cvt_pk_bf16_f32 v181, v74, v75
	v_cvt_pk_bf16_f32 v182, v76, v77
	v_cvt_pk_bf16_f32 v183, v78, v79
	v_permlane32_swap_b32_e32 v166, v168
	v_permlane32_swap_b32_e32 v167, v169
	v_permlane32_swap_b32_e32 v170, v172
	v_permlane32_swap_b32_e32 v171, v173
	v_permlane32_swap_b32_e32 v176, v178
	v_permlane32_swap_b32_e32 v177, v179
	v_permlane32_swap_b32_e32 v180, v182
	v_permlane32_swap_b32_e32 v181, v183
	s_add_u32 s31, s31, 1
	s_cmp_lt_u32 s31, 132
	s_cbranch_scc0 .Lda_skipk_2
	ds_read_b128 v[150:153], v204 offset:49152
	ds_read_b128 v[154:157], v204 offset:57344
	ds_read_b128 v[158:161], v205 offset:49152
	ds_read_b128 v[162:165], v205 offset:57344
	ds_read_b128 v[228:231], v206 offset:49152
	ds_read_b128 v[232:235], v206 offset:57344
	ds_read_b128 v[236:239], v207 offset:49152
	ds_read_b128 v[240:243], v207 offset:57344
.Lda_skipk_2:
	s_barrier
	s_setprio 3
	s_waitcnt vmcnt(4)
	ds_write_b128 v197, v[186:189] offset:16384
	ds_write_b128 v197, v[220:223] offset:24576
	ds_write_b128 v185, v[246:249] offset:16384
	ds_write_b128 v185, v[200:203] offset:24576
	s_waitcnt lgkmcnt(10)
	v_mfma_f32_32x32x16_bf16 v[80:95], v[150:153], v[130:133], 0
	v_mfma_f32_32x32x16_bf16 v[64:79], v[154:157], v[130:133], 0
	global_load_dwordx4 v[186:189], v184, s[16:17]
	global_load_dwordx4 v[220:223], v184, s[2:3]
	global_load_dwordx4 v[246:249], v184, s[14:15]
	global_load_dwordx4 v[200:203], v184, s[10:11]
	s_add_u32 s16, s16, 0x60000
	s_addc_u32 s17, s17, 0
	s_add_u32 s2, s2, 0x60000
	s_addc_u32 s3, s3, 0
	s_add_u32 s14, s14, 0x60000
	s_addc_u32 s15, s15, 0
	s_add_u32 s10, s10, 0x60000
	s_addc_u32 s11, s11, 0
	ds_read_b128 v[150:153], v208 offset:49152
	ds_read_b128 v[154:157], v208 offset:57344
	s_waitcnt lgkmcnt(10)
	v_mfma_f32_32x32x16_bf16 v[80:95], v[158:161], v[126:129], v[80:95]
	v_mfma_f32_32x32x16_bf16 v[64:79], v[162:165], v[126:129], v[64:79]
	ds_read_b128 v[158:161], v209 offset:49152
	ds_read_b128 v[162:165], v209 offset:57344
	s_waitcnt lgkmcnt(10)
	v_mfma_f32_32x32x16_bf16 v[80:95], v[228:231], v[122:125], v[80:95]
	v_mfma_f32_32x32x16_bf16 v[64:79], v[232:235], v[122:125], v[64:79]
	ds_read_b128 v[228:231], v210 offset:49152
	ds_read_b128 v[232:235], v210 offset:57344
	s_waitcnt lgkmcnt(10)
	v_mfma_f32_32x32x16_bf16 v[80:95], v[236:239], v[118:121], v[80:95]
	v_mfma_f32_32x32x16_bf16 v[64:79], v[240:243], v[118:121], v[64:79]
	ds_read_b128 v[236:239], v211 offset:49152
	ds_read_b128 v[240:243], v211 offset:57344
	s_waitcnt lgkmcnt(6)
	v_mfma_f32_32x32x16_bf16 v[80:95], v[150:153], v[114:117], v[80:95]
	v_mfma_f32_32x32x16_bf16 v[64:79], v[154:157], v[114:117], v[64:79]
	ds_read_b64_tr_b16 v[150:151], v196 offset:32768
	ds_read_b64_tr_b16 v[152:153], v196 offset:34816
	ds_read_b64_tr_b16 v[154:155], v196 offset:36864
	ds_read_b64_tr_b16 v[156:157], v196 offset:38912
	s_waitcnt lgkmcnt(8)
	v_mfma_f32_32x32x16_bf16 v[80:95], v[158:161], v[110:113], v[80:95]
	v_mfma_f32_32x32x16_bf16 v[64:79], v[162:165], v[110:113], v[64:79]
	ds_read_b64_tr_b16 v[158:159], v196 offset:40960
	ds_read_b64_tr_b16 v[160:161], v196 offset:43008
	ds_read_b64_tr_b16 v[162:163], v196 offset:45056
	ds_read_b64_tr_b16 v[164:165], v196 offset:47104
	s_waitcnt lgkmcnt(10)
	v_mfma_f32_32x32x16_bf16 v[80:95], v[228:231], v[106:109], v[80:95]
	v_mfma_f32_32x32x16_bf16 v[64:79], v[232:235], v[106:109], v[64:79]
	ds_read_b64_tr_b16 v[228:229], v196 offset:33280
	ds_read_b64_tr_b16 v[230:231], v196 offset:35328
	ds_read_b64_tr_b16 v[232:233], v196 offset:37376
	ds_read_b64_tr_b16 v[234:235], v196 offset:39424
	s_waitcnt lgkmcnt(12)
	v_mfma_f32_32x32x16_bf16 v[80:95], v[236:239], v[102:105], v[80:95]
	v_mfma_f32_32x32x16_bf16 v[64:79], v[240:243], v[102:105], v[64:79]
	ds_read_b64_tr_b16 v[236:237], v196 offset:41472
	ds_read_b64_tr_b16 v[238:239], v196 offset:43520
	s_waitcnt lgkmcnt(12)
	v_mfma_f32_32x32x16_bf16 v[0:15], v[166:169], v[150:153], v[0:15]
	ds_read_b64_tr_b16 v[240:241], v196 offset:45568
	ds_read_b64_tr_b16 v[242:243], v196 offset:47616
	s_waitcnt lgkmcnt(12)
	v_mfma_f32_32x32x16_bf16 v[0:15], v[170:173], v[154:157], v[0:15]
	ds_read_b64_tr_b16 v[150:151], v196 offset:33792
	ds_read_b64_tr_b16 v[152:153], v196 offset:35840
	s_waitcnt lgkmcnt(12)
	v_mfma_f32_32x32x16_bf16 v[0:15], v[176:179], v[158:161], v[0:15]
	ds_read_b64_tr_b16 v[154:155], v196 offset:37888
	ds_read_b64_tr_b16 v[156:157], v196 offset:39936
	s_waitcnt lgkmcnt(12)
	v_mfma_f32_32x32x16_bf16 v[0:15], v[180:183], v[162:165], v[0:15]
	ds_read_b64_tr_b16 v[158:159], v196 offset:41984
	ds_read_b64_tr_b16 v[160:161], v196 offset:44032
	s_waitcnt lgkmcnt(12)
	v_mfma_f32_32x32x16_bf16 v[48:63], v[166:169], v[228:231], v[48:63]
	ds_read_b64_tr_b16 v[162:163], v196 offset:46080
	ds_read_b64_tr_b16 v[164:165], v196 offset:48128
	s_waitcnt lgkmcnt(12)
	v_mfma_f32_32x32x16_bf16 v[48:63], v[170:173], v[232:235], v[48:63]
	ds_read_b64_tr_b16 v[228:229], v196 offset:34304
	ds_read_b64_tr_b16 v[230:231], v196 offset:36352
	s_waitcnt lgkmcnt(12)
	v_mfma_f32_32x32x16_bf16 v[48:63], v[176:179], v[236:239], v[48:63]
	ds_read_b64_tr_b16 v[232:233], v196 offset:38400
	ds_read_b64_tr_b16 v[234:235], v196 offset:40448
	s_waitcnt lgkmcnt(12)
	v_mfma_f32_32x32x16_bf16 v[48:63], v[180:183], v[240:243], v[48:63]
	ds_read_b64_tr_b16 v[236:237], v196 offset:42496
	ds_read_b64_tr_b16 v[238:239], v196 offset:44544
	s_waitcnt lgkmcnt(12)
	v_mfma_f32_32x32x16_bf16 v[32:47], v[166:169], v[150:153], v[32:47]
	ds_read_b64_tr_b16 v[240:241], v196 offset:46592
	ds_read_b64_tr_b16 v[242:243], v196 offset:48640
	s_waitcnt lgkmcnt(12)
	v_mfma_f32_32x32x16_bf16 v[32:47], v[170:173], v[154:157], v[32:47]
	s_waitcnt lgkmcnt(10)
	v_mfma_f32_32x32x16_bf16 v[32:47], v[176:179], v[158:161], v[32:47]
	s_waitcnt lgkmcnt(8)
	v_mfma_f32_32x32x16_bf16 v[32:47], v[180:183], v[162:165], v[32:47]
	s_waitcnt lgkmcnt(6)
	v_mfma_f32_32x32x16_bf16 v[16:31], v[166:169], v[228:231], v[16:31]
	s_waitcnt lgkmcnt(4)
	v_mfma_f32_32x32x16_bf16 v[16:31], v[170:173], v[232:235], v[16:31]
	s_waitcnt lgkmcnt(2)
	v_mfma_f32_32x32x16_bf16 v[16:31], v[176:179], v[236:239], v[16:31]
	s_waitcnt lgkmcnt(0)
	v_mfma_f32_32x32x16_bf16 v[16:31], v[180:183], v[240:243], v[16:31]
	s_setprio 0
	s_barrier
; __device__ __forceinline__ void partialSM(f32x16& p0, f32x16& p1, float& m_reg, float& mn, float& alpha) {
;     ...
;   float mnC = -mn * C;
; #pragma unroll
;   for (int r = 0; r < 16; ++r) p0[r] = fmaf(p0[r], C, mnC);
; #pragma unroll
;   for (int r = 0; r < 16; ++r) p1[r] = fmaf(p1[r], C, mnC);
; #pragma unroll
;   for (int r = 0; r < 16; ++r) p0[r] = __builtin_amdgcn_exp2f(p0[r]);
; }
; __device__ __forceinline__ void finishSM(f32x16& p0, f32x16& p1, float alpha, float& l_reg, bf16x8& pa0, bf16x8& pa1, bf16x8& pa2, bf16x8& pa3) {
; #pragma unroll
;   for (int r = 0; r < 16; ++r) p1[r] = __builtin_amdgcn_exp2f(p1[r]);
;   float ps = 0;
; #pragma unroll
;   for (int r = 0; r < 16; ++r) ps += p0[r];
; #pragma unroll
;   for (int r = 0; r < 16; ++r) ps += p1[r];
	v_fma_f32 v80, v80, s92, v214
	v_fma_f32 v81, v81, s92, v214
	v_fma_f32 v82, v82, s92, v214
	v_fma_f32 v83, v83, s92, v214
	v_fma_f32 v84, v84, s92, v214
	v_fma_f32 v85, v85, s92, v214
	v_fma_f32 v86, v86, s92, v214
	v_fma_f32 v87, v87, s92, v214
	v_fma_f32 v88, v88, s92, v214
	v_fma_f32 v89, v89, s92, v214
	v_fma_f32 v90, v90, s92, v214
	v_fma_f32 v91, v91, s92, v214
	v_fma_f32 v92, v92, s92, v214
	v_fma_f32 v93, v93, s92, v214
	v_fma_f32 v94, v94, s92, v214
	v_fma_f32 v95, v95, s92, v214
	v_fma_f32 v64, v64, s92, v214
	v_fma_f32 v65, v65, s92, v214
	v_fma_f32 v66, v66, s92, v214
	v_fma_f32 v67, v67, s92, v214
	v_fma_f32 v68, v68, s92, v214
	v_fma_f32 v69, v69, s92, v214
	v_fma_f32 v70, v70, s92, v214
	v_fma_f32 v71, v71, s92, v214
	v_fma_f32 v72, v72, s92, v214
	v_fma_f32 v73, v73, s92, v214
	v_fma_f32 v74, v74, s92, v214
	v_fma_f32 v75, v75, s92, v214
	v_fma_f32 v76, v76, s92, v214
	v_fma_f32 v77, v77, s92, v214
	v_fma_f32 v78, v78, s92, v214
	v_fma_f32 v79, v79, s92, v214
	v_exp_f32_e32 v80, v80
	v_exp_f32_e32 v81, v81
	v_exp_f32_e32 v82, v82
	v_exp_f32_e32 v83, v83
	v_exp_f32_e32 v84, v84
	v_exp_f32_e32 v85, v85
	v_exp_f32_e32 v86, v86
	v_exp_f32_e32 v87, v87
	v_exp_f32_e32 v88, v88
	v_exp_f32_e32 v89, v89
	v_exp_f32_e32 v90, v90
	v_exp_f32_e32 v91, v91
	v_exp_f32_e32 v92, v92
	v_exp_f32_e32 v93, v93
	v_exp_f32_e32 v94, v94
	v_exp_f32_e32 v95, v95
	v_exp_f32_e32 v64, v64
	v_exp_f32_e32 v65, v65
	v_exp_f32_e32 v66, v66
	v_exp_f32_e32 v67, v67
	v_exp_f32_e32 v68, v68
	v_exp_f32_e32 v69, v69
	v_exp_f32_e32 v70, v70
	v_exp_f32_e32 v71, v71
	v_exp_f32_e32 v72, v72
	v_exp_f32_e32 v73, v73
	v_exp_f32_e32 v74, v74
	v_exp_f32_e32 v75, v75
	v_exp_f32_e32 v76, v76
	v_exp_f32_e32 v77, v77
	v_exp_f32_e32 v78, v78
	v_exp_f32_e32 v79, v79
	v_add_f32_e32 v190, v80, v81
	v_add_f32_e32 v191, v82, v83
	v_add_f32_e32 v190, v190, v84
	v_add_f32_e32 v191, v191, v85
	v_add_f32_e32 v190, v190, v86
	v_add_f32_e32 v191, v191, v87
	v_add_f32_e32 v190, v190, v88
	v_add_f32_e32 v191, v191, v89
	v_add_f32_e32 v190, v190, v90
	v_add_f32_e32 v191, v191, v91
	v_add_f32_e32 v190, v190, v92
	v_add_f32_e32 v191, v191, v93
	v_add_f32_e32 v190, v190, v94
	v_add_f32_e32 v191, v191, v95
	v_add_f32_e32 v190, v190, v64
	v_add_f32_e32 v191, v191, v65
	v_add_f32_e32 v190, v190, v66
	v_add_f32_e32 v191, v191, v67
	v_add_f32_e32 v190, v190, v68
	v_add_f32_e32 v191, v191, v69
	v_add_f32_e32 v190, v190, v70
	v_add_f32_e32 v191, v191, v71
	v_add_f32_e32 v190, v190, v72
	v_add_f32_e32 v191, v191, v73
	v_add_f32_e32 v190, v190, v74
	v_add_f32_e32 v191, v191, v75
	v_add_f32_e32 v190, v190, v76
	v_add_f32_e32 v191, v191, v77
	v_add_f32_e32 v190, v190, v78
	v_add_f32_e32 v191, v191, v79
	v_add_f32_e32 v190, v190, v191
	v_cmp_ge_f32_e32 vcc, 0x453a4f54, v190
	s_nop 0
	s_cmp_eq_u64 vcc, exec
	s_cbranch_scc1 .Lda_pack_3
; __device__ __forceinline__ void partialSM(f32x16& p0, f32x16& p1, float& m_reg, float& mn, float& alpha) {
;   constexpr float C = SCALE * 1.4426950408889634f;
;   float pmax = p0[0];
; #pragma unroll
;   for (int r = 1; r < 16; ++r) pmax = fmaxf(pmax, p0[r]);
; #pragma unroll
;   for (int r = 0; r < 16; ++r) pmax = fmaxf(pmax, p1[r]);
;   { auto rr = __builtin_amdgcn_permlane32_swap(__float_as_uint(pmax), __float_as_uint(pmax), false, false);
;     pmax = fmaxf(__uint_as_float(rr[0]), __uint_as_float(rr[1])); }
;   if (__builtin_expect(__all(pmax - m_reg <= THR / SCALE), 1)) { mn = m_reg; alpha = 1.f; }
;   else { mn = fmaxf(m_reg, pmax); alpha = __builtin_amdgcn_exp2f((m_reg - mn) * C); m_reg = mn; }
; __device__ __forceinline__ void qkt(f32x16& p0, f32x16& p1, const bf16_t* Ks, const bf16x8* qr, int r32, int hi) {
;   p0 = f32x16{}; p1 = f32x16{};
; #pragma unroll
;   for (int d0 = 0; d0 < 8; ++d0) { int cb = (d0 * 16 + hi * 8) * 2;
;     bf16x8 b0 = *reinterpret_cast<const bf16x8*>((const char*)Ks + KSWZ(r32, cb));
;     bf16x8 b1 = *reinterpret_cast<const bf16x8*>((const char*)Ks + KSWZ(32 + r32, cb));
;     p0 = __builtin_amdgcn_mfma_f32_32x32x16_bf16(b0, qr[d0], p0, 0, 0, 0);
;     p1 = __builtin_amdgcn_mfma_f32_32x32x16_bf16(b1, qr[d0], p1, 0, 0, 0); }
; }
	ds_read_b128 v[150:153], v204 offset:49152
	ds_read_b128 v[154:157], v204 offset:57344
	ds_read_b128 v[158:161], v205 offset:49152
	ds_read_b128 v[162:165], v205 offset:57344
	ds_read_b128 v[228:231], v206 offset:49152
	ds_read_b128 v[232:235], v206 offset:57344
	ds_read_b128 v[236:239], v207 offset:49152
	ds_read_b128 v[240:243], v207 offset:57344
	s_waitcnt lgkmcnt(6)
	v_mfma_f32_32x32x16_bf16 v[80:95], v[150:153], v[130:133], 0
	v_mfma_f32_32x32x16_bf16 v[64:79], v[154:157], v[130:133], 0
	ds_read_b128 v[150:153], v208 offset:49152
	ds_read_b128 v[154:157], v208 offset:57344
	s_waitcnt lgkmcnt(6)
	v_mfma_f32_32x32x16_bf16 v[80:95], v[158:161], v[126:129], v[80:95]
	v_mfma_f32_32x32x16_bf16 v[64:79], v[162:165], v[126:129], v[64:79]
	ds_read_b128 v[158:161], v209 offset:49152
	ds_read_b128 v[162:165], v209 offset:57344
	s_waitcnt lgkmcnt(6)
	v_mfma_f32_32x32x16_bf16 v[80:95], v[228:231], v[122:125], v[80:95]
	v_mfma_f32_32x32x16_bf16 v[64:79], v[232:235], v[122:125], v[64:79]
	ds_read_b128 v[228:231], v210 offset:49152
	ds_read_b128 v[232:235], v210 offset:57344
	s_waitcnt lgkmcnt(6)
	v_mfma_f32_32x32x16_bf16 v[80:95], v[236:239], v[118:121], v[80:95]
	v_mfma_f32_32x32x16_bf16 v[64:79], v[240:243], v[118:121], v[64:79]
	ds_read_b128 v[236:239], v211 offset:49152
	ds_read_b128 v[240:243], v211 offset:57344
	s_waitcnt lgkmcnt(6)
	v_mfma_f32_32x32x16_bf16 v[80:95], v[150:153], v[114:117], v[80:95]
	v_mfma_f32_32x32x16_bf16 v[64:79], v[154:157], v[114:117], v[64:79]
	s_waitcnt lgkmcnt(4)
	v_mfma_f32_32x32x16_bf16 v[80:95], v[158:161], v[110:113], v[80:95]
	v_mfma_f32_32x32x16_bf16 v[64:79], v[162:165], v[110:113], v[64:79]
	s_waitcnt lgkmcnt(2)
	v_mfma_f32_32x32x16_bf16 v[80:95], v[228:231], v[106:109], v[80:95]
	v_mfma_f32_32x32x16_bf16 v[64:79], v[232:235], v[106:109], v[64:79]
	s_waitcnt lgkmcnt(0)
	v_mfma_f32_32x32x16_bf16 v[80:95], v[236:239], v[102:105], v[80:95]
	v_mfma_f32_32x32x16_bf16 v[64:79], v[240:243], v[102:105], v[64:79]
	s_nop 12
	v_max3_f32 v190, v80, v81, v82
	v_max3_f32 v191, v64, v65, v66
	v_max3_f32 v190, v190, v83, v84
	v_max3_f32 v191, v191, v67, v68
	v_max3_f32 v190, v190, v85, v86
	v_max3_f32 v191, v191, v69, v70
	v_max3_f32 v190, v190, v87, v88
	v_max3_f32 v191, v191, v71, v72
	v_max3_f32 v190, v190, v89, v90
	v_max3_f32 v191, v191, v73, v74
	v_max3_f32 v190, v190, v91, v92
	v_max3_f32 v191, v191, v75, v76
	v_max3_f32 v190, v190, v93, v94
	v_max3_f32 v191, v191, v77, v78
	v_max3_f32 v190, v190, v95, v79
	v_max_f32_e32 v190, v190, v191
	v_mov_b32_e32 v191, v190
	s_nop 1
	v_permlane32_swap_b32_e32 v190, v191
	s_nop 0
	v_max_f32_e32 v212, v190, v191
	v_sub_f32_e32 v215, v212, v174
	v_cmp_ge_f32_e32 vcc, s86, v215
	s_nop 0
	s_cmp_eq_u64 vcc, exec
	s_cbranch_scc1 .Lda_slow2_3
	v_max_f32_e32 v191, v174, v212
	v_sub_f32_e32 v215, v174, v191
	v_mul_f32_e32 v215, s92, v215
	v_exp_f32_e32 v213, v215
	v_mov_b32_e32 v174, v191
	v_mul_f32_e32 v214, 0xbe0293ee, v174
	v_mul_f32_e32 v175, v175, v213
	s_and_saveexec_b64 s[12:13], s[40:41]
	ds_write_b32 v199, v213 offset:128
	s_or_b64 exec, exec, s[12:13]
	s_waitcnt lgkmcnt(0)
	v_add_u32_e32 v215, v99, v96
	ds_read_b128 v[228:231], v215 offset:128
	ds_read_b128 v[232:235], v215 offset:160
	ds_read_b128 v[236:239], v215 offset:192
	ds_read_b128 v[240:243], v215 offset:224
	s_waitcnt lgkmcnt(0)
	v_pk_mul_f32 v[0:1], v[0:1], v[228:229]
	v_pk_mul_f32 v[2:3], v[2:3], v[230:231]
	v_pk_mul_f32 v[4:5], v[4:5], v[232:233]
	v_pk_mul_f32 v[6:7], v[6:7], v[234:235]
	v_pk_mul_f32 v[8:9], v[8:9], v[236:237]
	v_pk_mul_f32 v[10:11], v[10:11], v[238:239]
	v_pk_mul_f32 v[12:13], v[12:13], v[240:241]
	v_pk_mul_f32 v[14:15], v[14:15], v[242:243]
	v_pk_mul_f32 v[48:49], v[48:49], v[228:229]
	v_pk_mul_f32 v[50:51], v[50:51], v[230:231]
	v_pk_mul_f32 v[52:53], v[52:53], v[232:233]
	v_pk_mul_f32 v[54:55], v[54:55], v[234:235]
	v_pk_mul_f32 v[56:57], v[56:57], v[236:237]
	v_pk_mul_f32 v[58:59], v[58:59], v[238:239]
	v_pk_mul_f32 v[60:61], v[60:61], v[240:241]
	v_pk_mul_f32 v[62:63], v[62:63], v[242:243]
	v_pk_mul_f32 v[32:33], v[32:33], v[228:229]
	v_pk_mul_f32 v[34:35], v[34:35], v[230:231]
	v_pk_mul_f32 v[36:37], v[36:37], v[232:233]
	v_pk_mul_f32 v[38:39], v[38:39], v[234:235]
	v_pk_mul_f32 v[40:41], v[40:41], v[236:237]
	v_pk_mul_f32 v[42:43], v[42:43], v[238:239]
	v_pk_mul_f32 v[44:45], v[44:45], v[240:241]
	v_pk_mul_f32 v[46:47], v[46:47], v[242:243]
	v_pk_mul_f32 v[16:17], v[16:17], v[228:229]
	v_pk_mul_f32 v[18:19], v[18:19], v[230:231]
	v_pk_mul_f32 v[20:21], v[20:21], v[232:233]
	v_pk_mul_f32 v[22:23], v[22:23], v[234:235]
	v_pk_mul_f32 v[24:25], v[24:25], v[236:237]
	v_pk_mul_f32 v[26:27], v[26:27], v[238:239]
	v_pk_mul_f32 v[28:29], v[28:29], v[240:241]
	v_pk_mul_f32 v[30:31], v[30:31], v[242:243]

; __device__ __forceinline__ void finishSM(f32x16& p0, f32x16& p1, float alpha, float& l_reg, bf16x8& pa0, bf16x8& pa1, bf16x8& pa2, bf16x8& pa3) {
;     ...
;   l_reg = l_reg * alpha + ps;
;     ...
;   PK4(p0, 0, pa0); PK4(p0, 8, pa1); PK4(p1, 0, pa2); PK4(p1, 8, pa3);
.Lda_pack_3:
	v_add_f32_e32 v175, v175, v190
	v_cvt_pk_bf16_f32 v166, v80, v81
	v_cvt_pk_bf16_f32 v167, v82, v83
	v_cvt_pk_bf16_f32 v168, v84, v85
	v_cvt_pk_bf16_f32 v169, v86, v87
	v_cvt_pk_bf16_f32 v170, v88, v89
	v_cvt_pk_bf16_f32 v171, v90, v91
	v_cvt_pk_bf16_f32 v172, v92, v93
	v_cvt_pk_bf16_f32 v173, v94, v95
	v_cvt_pk_bf16_f32 v176, v64, v65
	v_cvt_pk_bf16_f32 v177, v66, v67
	v_cvt_pk_bf16_f32 v178, v68, v69
	v_cvt_pk_bf16_f32 v179, v70, v71
	v_cvt_pk_bf16_f32 v180, v72, v73
	v_cvt_pk_bf16_f32 v181, v74, v75
	v_cvt_pk_bf16_f32 v182, v76, v77
	v_cvt_pk_bf16_f32 v183, v78, v79
	v_permlane32_swap_b32_e32 v166, v168
	v_permlane32_swap_b32_e32 v167, v169
	v_permlane32_swap_b32_e32 v170, v172
	v_permlane32_swap_b32_e32 v171, v173
	v_permlane32_swap_b32_e32 v176, v178
	v_permlane32_swap_b32_e32 v177, v179
	v_permlane32_swap_b32_e32 v180, v182
	v_permlane32_swap_b32_e32 v181, v183
	s_add_u32 s31, s31, 1
	s_cmp_lt_u32 s31, 132
	s_cbranch_scc0 .Lda_skipk_3
	ds_read_b128 v[150:153], v204 offset:0
	ds_read_b128 v[154:157], v204 offset:8192
	ds_read_b128 v[158:161], v205 offset:0
	ds_read_b128 v[162:165], v205 offset:8192
	ds_read_b128 v[228:231], v206 offset:0
	ds_read_b128 v[232:235], v206 offset:8192
	ds_read_b128 v[236:239], v207 offset:0
	ds_read_b128 v[240:243], v207 offset:8192
